# GEMM K-loops: back edge rotated so the loop-back barrier is the loop head (branch taken before the barrier wait), exit path keeps its own barrier
# baseline (speedup 1.0000x reference)
; DI void gemm_phase(LAS unsigned char* lds, const Gemm g, const StaticOrder& S, const EpiBf16& E) {
;     ...
;         const bool has_next = S.next(ui + 1, nxt);
;         const char* nA = has_next ? (const char*)g.A + (size_t)nxt.pm * tstep : cA; const char* nB = has_next ? (const char*)g.Bt + (size_t)nxt.pn * tstep : cB;
;         for (int t = 0; t < nt; t += 2) {
;             const bool last = (t == nt - 2);
;             const char* a1 = cA + (size_t)(t + 1) * kstep;
;             const char* a2 = last ? nA : cA + (size_t)(t + 2) * kstep; const char* b2 = last ? nB : cB + (size_t)(t + 2) * kstep;
;             const char* a3 = a2 + kstep; const char* b3 = b2 + kstep;
;     ...
; #pragma unroll
;         for (int a = 0; a < 2; ++a)
; #pragma unroll
;             for (int b = 0; b < 2; ++b)
; #pragma unroll
;                 for (int m = 0; m < 4; ++m)
; #pragma unroll
;                     for (int n = 0; n < 2; ++n) acc[a][b][m][n] = (f32x4){0.f, 0.f, 0.f, 0.f};
;         cur = nxt; cA = nA; cB = nB; ++ui;
.LBB0_180:
	v_mov_b64_e32 v[0:1], 0x3f0
	s_ashr_i32 s45, s44, 31
	v_cmp_lt_i64_e32 vcc, s[46:47], v[0:1]
	s_lshl_b64 s[46:47], s[44:45], 20
	s_add_u32 s46, s21, s46
	s_addc_u32 s47, s22, s47
	s_and_b64 s[48:49], vcc, exec
	s_cselect_b32 s45, s47, s51
	s_cselect_b32 s69, s46, s50
	s_ashr_i32 s43, s42, 31
	s_lshl_b64 s[48:49], s[42:43], 20
	s_add_u32 s48, s24, s48
	s_addc_u32 s49, s26, s49
	s_and_b64 s[54:55], vcc, exec
	s_cselect_b32 s43, s49, s53
	s_cselect_b32 s70, s48, s52
	s_add_u32 s50, s50, 0x80080
	s_addc_u32 s51, s51, 0
	s_add_u32 s71, s52, 0x100
	v_mov_b32_e32 v0, 0
	s_addc_u32 s72, s53, 0
	s_mov_b32 s73, -2
	v_mov_b32_e32 v1, v0
	v_mov_b32_e32 v2, v0
	v_mov_b32_e32 v3, v0
	v_mov_b32_e32 v4, v0
	v_mov_b32_e32 v5, v0
	v_mov_b32_e32 v6, v0
	v_mov_b32_e32 v7, v0
	v_mov_b32_e32 v8, v0
	v_mov_b32_e32 v9, v0
	v_mov_b32_e32 v10, v0
	v_mov_b32_e32 v11, v0
	v_mov_b32_e32 v12, v0
	v_mov_b32_e32 v13, v0
	v_mov_b32_e32 v14, v0
	v_mov_b32_e32 v15, v0
	v_mov_b32_e32 v24, v0
	v_mov_b32_e32 v25, v0
	v_mov_b32_e32 v26, v0
	v_mov_b32_e32 v27, v0
	v_mov_b32_e32 v28, v0
	v_mov_b32_e32 v29, v0
	v_mov_b32_e32 v30, v0
	v_mov_b32_e32 v31, v0
	v_mov_b32_e32 v40, v0
	v_mov_b32_e32 v41, v0
	v_mov_b32_e32 v42, v0
	v_mov_b32_e32 v43, v0
	v_mov_b32_e32 v44, v0
	v_mov_b32_e32 v45, v0
	v_mov_b32_e32 v46, v0
	v_mov_b32_e32 v47, v0
	v_mov_b32_e32 v16, v0
	v_mov_b32_e32 v17, v0
	v_mov_b32_e32 v18, v0
	v_mov_b32_e32 v19, v0
	v_mov_b32_e32 v20, v0
	v_mov_b32_e32 v21, v0
	v_mov_b32_e32 v22, v0
	v_mov_b32_e32 v23, v0
	v_mov_b32_e32 v32, v0
	v_mov_b32_e32 v33, v0
	v_mov_b32_e32 v34, v0
	v_mov_b32_e32 v35, v0
	v_mov_b32_e32 v36, v0
	v_mov_b32_e32 v37, v0
	v_mov_b32_e32 v38, v0
	v_mov_b32_e32 v39, v0
	v_mov_b32_e32 v48, v0
	v_mov_b32_e32 v49, v0
	v_mov_b32_e32 v50, v0
	v_mov_b32_e32 v51, v0
	v_mov_b32_e32 v52, v0
	v_mov_b32_e32 v53, v0
	v_mov_b32_e32 v54, v0
	v_mov_b32_e32 v55, v0
	v_mov_b32_e32 v56, v0
	v_mov_b32_e32 v57, v0
	v_mov_b32_e32 v58, v0
	v_mov_b32_e32 v59, v0
	v_mov_b32_e32 v60, v0
	v_mov_b32_e32 v61, v0
	v_mov_b32_e32 v62, v0
	v_mov_b32_e32 v63, v0
	v_mov_b32_e32 v64, v0
	v_mov_b32_e32 v65, v0
	v_mov_b32_e32 v66, v0
	v_mov_b32_e32 v67, v0
	v_mov_b32_e32 v68, v0
	v_mov_b32_e32 v69, v0
	v_mov_b32_e32 v70, v0
	v_mov_b32_e32 v71, v0
	v_mov_b32_e32 v72, v0
	v_mov_b32_e32 v73, v0
	v_mov_b32_e32 v74, v0
	v_mov_b32_e32 v75, v0
	v_mov_b32_e32 v76, v0
	v_mov_b32_e32 v77, v0
	v_mov_b32_e32 v78, v0
	v_mov_b32_e32 v79, v0
	v_mov_b32_e32 v88, v0
	v_mov_b32_e32 v89, v0
	v_mov_b32_e32 v90, v0
	v_mov_b32_e32 v91, v0
	v_mov_b32_e32 v92, v0
	v_mov_b32_e32 v93, v0
	v_mov_b32_e32 v94, v0
	v_mov_b32_e32 v95, v0
	v_mov_b32_e32 v104, v0
	v_mov_b32_e32 v105, v0
	v_mov_b32_e32 v106, v0
	v_mov_b32_e32 v107, v0
	v_mov_b32_e32 v108, v0
	v_mov_b32_e32 v109, v0
	v_mov_b32_e32 v110, v0
	v_mov_b32_e32 v111, v0
	v_mov_b32_e32 v80, v0
	v_mov_b32_e32 v81, v0
	v_mov_b32_e32 v82, v0
	v_mov_b32_e32 v83, v0
	v_mov_b32_e32 v84, v0
	v_mov_b32_e32 v85, v0
	v_mov_b32_e32 v86, v0
	v_mov_b32_e32 v87, v0
	v_mov_b32_e32 v96, v0
	v_mov_b32_e32 v97, v0
	v_mov_b32_e32 v98, v0
	v_mov_b32_e32 v99, v0
	v_mov_b32_e32 v100, v0
	v_mov_b32_e32 v101, v0
	v_mov_b32_e32 v102, v0
	v_mov_b32_e32 v103, v0
	v_mov_b32_e32 v112, v0
	v_mov_b32_e32 v113, v0
	v_mov_b32_e32 v114, v0
	v_mov_b32_e32 v115, v0
	v_mov_b32_e32 v116, v0
	v_mov_b32_e32 v117, v0
	v_mov_b32_e32 v118, v0
	v_mov_b32_e32 v119, v0
	v_mov_b32_e32 v120, v0
	v_mov_b32_e32 v121, v0
	v_mov_b32_e32 v122, v0
	v_mov_b32_e32 v123, v0
	v_mov_b32_e32 v124, v0
	v_mov_b32_e32 v125, v0
	v_mov_b32_e32 v126, v0
	v_mov_b32_e32 v127, v0
	s_branch .Lk181_first

; #define PG8_STAGE(bufoff, gbase, voff) do { _Pragma("unroll") for (int _i = 0; _i < 2; ++_i) \
;         __builtin_amdgcn_global_load_lds((const unsigned*)((const char*)(gbase) + (voff)[_i]), (LAS unsigned*)(lds + (bufoff) + ldsw + _i * 8192), 16, 0, 0); } while (0)
; #define PG8_LDA(dst, b, h) do { _Pragma("unroll") for (int m = 0; m < 4; ++m) _Pragma("unroll") for (int k = 0; k < 2; ++k) dst[m][k] = *(const LAS bf16x8*)(lds + PG8_SA(b, h) + aoff + m * 2048 + k * 1024); } while (0)
; #define PG8_LDB(dst, b, h) do { _Pragma("unroll") for (int n = 0; n < 2; ++n) _Pragma("unroll") for (int k = 0; k < 2; ++k) dst[n][k] = *(const LAS bf16x8*)(lds + PG8_SB(b, h) + boff + n * 2048 + k * 1024); } while (0)
; #define PG8_MMA(ai, bj, At, Bt) do { __builtin_amdgcn_s_setprio(1); _Pragma("unroll") for (int m = 0; m < 4; ++m) _Pragma("unroll") for (int n = 0; n < 2; ++n) _Pragma("unroll") for (int k = 0; k < 2; ++k) \
;         acc[ai][bj][m][n] = __builtin_amdgcn_mfma_f32_16x16x32_bf16(Bt[n][k], At[m][k], acc[ai][bj][m][n], 0, 0, 0); __builtin_amdgcn_s_setprio(0); } while (0)
; #define PG8_WAIT_L(n) asm volatile("s_waitcnt lgkmcnt(" #n ")" ::: "memory")
; #define PG8_BAR __builtin_amdgcn_s_barrier()
; #define PG8_SCHED __builtin_amdgcn_sched_barrier(0)
; DI void gemm_phase(LAS unsigned char* lds, const Gemm g, const StaticOrder& S, const EpiBf16& E) {
;     ...
;         for (int t = 0; t < nt; t += 2) {
;             const bool last = (t == nt - 2);
;             const char* a1 = cA + (size_t)(t + 1) * kstep;
;             const char* a2 = last ? nA : cA + (size_t)(t + 2) * kstep; const char* b2 = last ? nB : cB + (size_t)(t + 2) * kstep;
;             const char* a3 = a2 + kstep; const char* b3 = b2 + kstep;
;             PG8_LDB(B0, 0, 0); PG8_SCHED; PG8_LDA(At, 0, 0); PG8_STAGE(PG8_SA(1, 1), a1 + hstep, voffA);
;             PG8_WAIT_L(8); PG8_BAR; PG8_WAIT_L(0); PG8_MMA(0, 0, At, B0); PG8_BAR; PG8_SCHED;
;             PG8_LDB(B1, 0, 1); PG8_STAGE(PG8_SB(0, 0), b2, voffB);
;             PG8_BAR; PG8_WAIT_L(0); PG8_MMA(0, 1, At, B1); PG8_BAR;
;             PG8_LDA(At, 0, 1); PG8_STAGE(PG8_SA(0, 0), a2, voffA);
;             PG8_BAR; PG8_WAIT_L(0); PG8_MMA(1, 0, At, B0); PG8_BAR; PG8_SCHED;
.Lk181_first:
	ds_read_b128 v[160:163], v155
	ds_read_b128 v[184:187], v155 offset:1024
	ds_read_b128 v[188:191], v155 offset:2048
	ds_read_b128 v[192:195], v155 offset:3072
	s_add_u32 s4, s50, 0xfff80080
	s_addc_u32 s5, s51, -1
	s_cmp_eq_u32 s73, 28
	s_cselect_b32 s55, s45, s5
	s_cselect_b32 s54, s69, s4
	s_cselect_b32 s53, s43, s72
	s_cselect_b32 s52, s70, s71
	v_lshl_add_u64 v[164:165], s[50:51], 0, v[148:149]
	s_add_i32 m0, s31, 0xc000
	ds_read_b128 v[196:199], v156
	ds_read_b128 v[200:203], v156 offset:1024
	ds_read_b128 v[204:207], v156 offset:2048
	ds_read_b128 v[208:211], v156 offset:3072
	ds_read_b128 v[212:215], v156 offset:4096
	ds_read_b128 v[216:219], v156 offset:5120
	ds_read_b128 v[224:227], v156 offset:6144
	ds_read_b128 v[228:231], v156 offset:7168
	global_load_lds_dwordx4 v[164:165], off
	v_lshl_add_u64 v[164:165], s[50:51], 0, v[150:151]
	s_add_i32 m0, s31, 0xe000
	s_nop 0
	global_load_lds_dwordx4 v[164:165], off
	s_waitcnt lgkmcnt(8)
	s_barrier
	s_waitcnt lgkmcnt(0)
	s_setprio 1
	s_waitcnt lgkmcnt(0)
	v_mfma_f32_16x16x32_bf16 v[124:127], v[160:163], v[196:199], v[124:127]
	v_mfma_f32_16x16x32_bf16 v[120:123], v[188:191], v[196:199], v[120:123]
	v_mfma_f32_16x16x32_bf16 v[116:119], v[160:163], v[204:207], v[116:119]
	v_mfma_f32_16x16x32_bf16 v[112:115], v[188:191], v[204:207], v[112:115]
	v_mfma_f32_16x16x32_bf16 v[100:103], v[160:163], v[212:215], v[100:103]
	v_mfma_f32_16x16x32_bf16 v[96:99], v[188:191], v[212:215], v[96:99]
	v_mfma_f32_16x16x32_bf16 v[84:87], v[160:163], v[224:227], v[84:87]
	v_mfma_f32_16x16x32_bf16 v[80:83], v[188:191], v[224:227], v[80:83]
	v_mfma_f32_16x16x32_bf16 v[124:127], v[184:187], v[200:203], v[124:127]
	v_mfma_f32_16x16x32_bf16 v[120:123], v[192:195], v[200:203], v[120:123]
	v_mfma_f32_16x16x32_bf16 v[116:119], v[184:187], v[208:211], v[116:119]
	v_mfma_f32_16x16x32_bf16 v[112:115], v[192:195], v[208:211], v[112:115]
	v_mfma_f32_16x16x32_bf16 v[100:103], v[184:187], v[216:219], v[100:103]
	v_mfma_f32_16x16x32_bf16 v[96:99], v[192:195], v[216:219], v[96:99]
	v_mfma_f32_16x16x32_bf16 v[84:87], v[184:187], v[228:231], v[84:87]
	v_mfma_f32_16x16x32_bf16 v[80:83], v[192:195], v[228:231], v[80:83]
	s_setprio 0
	s_barrier
	s_mov_b32 m0, s28
	v_lshl_add_u64 v[164:165], s[52:53], 0, v[132:133]
	ds_read_b128 v[232:235], v157
	ds_read_b128 v[236:239], v157 offset:1024
	ds_read_b128 v[240:243], v157 offset:2048
	ds_read_b128 v[244:247], v157 offset:3072
	global_load_lds_dwordx4 v[164:165], off
	v_lshl_add_u64 v[248:249], s[52:53], 0, v[142:143]
	s_mov_b32 m0, s30
	s_nop 0
	global_load_lds_dwordx4 v[248:249], off
	s_barrier
	s_waitcnt lgkmcnt(0)
	s_setprio 1
	s_waitcnt lgkmcnt(0)
	v_mfma_f32_16x16x32_bf16 v[108:111], v[232:235], v[196:199], v[108:111]
	v_mfma_f32_16x16x32_bf16 v[104:107], v[240:243], v[196:199], v[104:107]
	v_mfma_f32_16x16x32_bf16 v[92:95], v[232:235], v[204:207], v[92:95]
	v_mfma_f32_16x16x32_bf16 v[88:91], v[240:243], v[204:207], v[88:91]
	v_mfma_f32_16x16x32_bf16 v[76:79], v[232:235], v[212:215], v[76:79]
	v_mfma_f32_16x16x32_bf16 v[72:75], v[240:243], v[212:215], v[72:75]
	v_mfma_f32_16x16x32_bf16 v[68:71], v[232:235], v[224:227], v[68:71]
	v_mfma_f32_16x16x32_bf16 v[64:67], v[240:243], v[224:227], v[64:67]
	v_mfma_f32_16x16x32_bf16 v[108:111], v[236:239], v[200:203], v[108:111]
	v_mfma_f32_16x16x32_bf16 v[104:107], v[244:247], v[200:203], v[104:107]
	v_mfma_f32_16x16x32_bf16 v[92:95], v[236:239], v[208:211], v[92:95]
	v_mfma_f32_16x16x32_bf16 v[88:91], v[244:247], v[208:211], v[88:91]
	v_mfma_f32_16x16x32_bf16 v[76:79], v[236:239], v[216:219], v[76:79]
	v_mfma_f32_16x16x32_bf16 v[72:75], v[244:247], v[216:219], v[72:75]
	v_mfma_f32_16x16x32_bf16 v[68:71], v[236:239], v[228:231], v[68:71]
	v_mfma_f32_16x16x32_bf16 v[64:67], v[244:247], v[228:231], v[64:67]
	s_setprio 0
	s_mov_b32 m0, s31
	v_lshl_add_u64 v[250:251], s[54:55], 0, v[146:147]
	s_barrier
	ds_read_b128 v[196:199], v156 offset:16384
	ds_read_b128 v[200:203], v156 offset:17408
	ds_read_b128 v[204:207], v156 offset:18432
	ds_read_b128 v[208:211], v156 offset:19456
	ds_read_b128 v[212:215], v156 offset:20480
	ds_read_b128 v[216:219], v156 offset:21504
	ds_read_b128 v[224:227], v156 offset:22528
	ds_read_b128 v[228:231], v156 offset:23552
	global_load_lds_dwordx4 v[250:251], off
	v_lshl_add_u64 v[134:135], s[54:55], 0, v[144:145]
	s_mov_b32 m0, s41
	s_nop 0
	global_load_lds_dwordx4 v[134:135], off
	s_barrier
	s_waitcnt lgkmcnt(0)
	s_setprio 1
	s_waitcnt lgkmcnt(0)
	v_mfma_f32_16x16x32_bf16 v[60:63], v[160:163], v[196:199], v[60:63]
	v_mfma_f32_16x16x32_bf16 v[56:59], v[188:191], v[196:199], v[56:59]
	v_mfma_f32_16x16x32_bf16 v[52:55], v[160:163], v[204:207], v[52:55]
	v_mfma_f32_16x16x32_bf16 v[48:51], v[188:191], v[204:207], v[48:51]
	v_mfma_f32_16x16x32_bf16 v[36:39], v[160:163], v[212:215], v[36:39]
	v_mfma_f32_16x16x32_bf16 v[32:35], v[188:191], v[212:215], v[32:35]
	v_mfma_f32_16x16x32_bf16 v[20:23], v[160:163], v[224:227], v[20:23]
	v_mfma_f32_16x16x32_bf16 v[16:19], v[188:191], v[224:227], v[16:19]
	v_mfma_f32_16x16x32_bf16 v[60:63], v[184:187], v[200:203], v[60:63]
	v_mfma_f32_16x16x32_bf16 v[56:59], v[192:195], v[200:203], v[56:59]
	v_mfma_f32_16x16x32_bf16 v[52:55], v[184:187], v[208:211], v[52:55]
	v_mfma_f32_16x16x32_bf16 v[48:51], v[192:195], v[208:211], v[48:51]
	v_mfma_f32_16x16x32_bf16 v[36:39], v[184:187], v[216:219], v[36:39]
	v_mfma_f32_16x16x32_bf16 v[32:35], v[192:195], v[216:219], v[32:35]
	v_mfma_f32_16x16x32_bf16 v[20:23], v[184:187], v[228:231], v[20:23]
	v_mfma_f32_16x16x32_bf16 v[16:19], v[192:195], v[228:231], v[16:19]
	s_setprio 0
	s_barrier
; #define PG8_STAGE(bufoff, gbase, voff) do { _Pragma("unroll") for (int _i = 0; _i < 2; ++_i) \
;         __builtin_amdgcn_global_load_lds((const unsigned*)((const char*)(gbase) + (voff)[_i]), (LAS unsigned*)(lds + (bufoff) + ldsw + _i * 8192), 16, 0, 0); } while (0)
; #define PG8_LDA(dst, b, h) do { _Pragma("unroll") for (int m = 0; m < 4; ++m) _Pragma("unroll") for (int k = 0; k < 2; ++k) dst[m][k] = *(const LAS bf16x8*)(lds + PG8_SA(b, h) + aoff + m * 2048 + k * 1024); } while (0)
; #define PG8_LDB(dst, b, h) do { _Pragma("unroll") for (int n = 0; n < 2; ++n) _Pragma("unroll") for (int k = 0; k < 2; ++k) dst[n][k] = *(const LAS bf16x8*)(lds + PG8_SB(b, h) + boff + n * 2048 + k * 1024); } while (0)
; #define PG8_MMA(ai, bj, At, Bt) do { __builtin_amdgcn_s_setprio(1); _Pragma("unroll") for (int m = 0; m < 4; ++m) _Pragma("unroll") for (int n = 0; n < 2; ++n) _Pragma("unroll") for (int k = 0; k < 2; ++k) \
;         acc[ai][bj][m][n] = __builtin_amdgcn_mfma_f32_16x16x32_bf16(Bt[n][k], At[m][k], acc[ai][bj][m][n], 0, 0, 0); __builtin_amdgcn_s_setprio(0); } while (0)
; #define PG8_WAIT_V(n) asm volatile("s_waitcnt vmcnt(" #n ")" ::: "memory")
; #define PG8_WAIT_L(n) asm volatile("s_waitcnt lgkmcnt(" #n ")" ::: "memory")
; #define PG8_BAR __builtin_amdgcn_s_barrier()
; #define PG8_SCHED __builtin_amdgcn_sched_barrier(0)
; DI void gemm_phase(LAS unsigned char* lds, const Gemm g, const StaticOrder& S, const EpiBf16& E) {
;     ...
;             PG8_STAGE(PG8_SB(0, 1), b2 + hstep, voffB);
;             PG8_WAIT_V(6); PG8_BAR; PG8_MMA(1, 1, At, B1); PG8_BAR;
;             PG8_LDB(B0, 1, 0); PG8_SCHED; PG8_LDA(At, 1, 0); PG8_STAGE(PG8_SA(0, 1), a2 + hstep, voffA);
;             PG8_WAIT_L(8); PG8_BAR; PG8_WAIT_L(0); PG8_MMA(0, 0, At, B0); PG8_BAR; PG8_SCHED;
;             PG8_LDB(B1, 1, 1); PG8_STAGE(PG8_SB(1, 0), b3, voffB);
;             PG8_BAR; PG8_WAIT_L(0); PG8_MMA(0, 1, At, B1); PG8_BAR;
;             PG8_LDA(At, 1, 1); PG8_STAGE(PG8_SA(1, 0), a3, voffA);
;             PG8_BAR; PG8_WAIT_L(0); PG8_MMA(1, 0, At, B0); PG8_BAR; PG8_SCHED;
;             PG8_STAGE(PG8_SB(1, 1), b3 + hstep, voffB);
	s_add_u32 s74, s52, 0x80000
	s_addc_u32 s75, s53, 0
	s_mov_b32 m0, s56
	v_lshl_add_u64 v[160:161], s[74:75], 0, v[132:133]
	global_load_lds_dwordx4 v[160:161], off
	v_lshl_add_u64 v[160:161], s[74:75], 0, v[142:143]
	s_mov_b32 m0, s57
	s_nop 0
	global_load_lds_dwordx4 v[160:161], off
	s_waitcnt vmcnt(6)
	s_barrier
	s_setprio 1
	v_mfma_f32_16x16x32_bf16 v[44:47], v[232:235], v[196:199], v[44:47]
	v_mfma_f32_16x16x32_bf16 v[40:43], v[240:243], v[196:199], v[40:43]
	v_mfma_f32_16x16x32_bf16 v[28:31], v[232:235], v[204:207], v[28:31]
	v_mfma_f32_16x16x32_bf16 v[24:27], v[240:243], v[204:207], v[24:27]
	v_mfma_f32_16x16x32_bf16 v[12:15], v[232:235], v[212:215], v[12:15]
	v_mfma_f32_16x16x32_bf16 v[8:11], v[240:243], v[212:215], v[8:11]
	v_mfma_f32_16x16x32_bf16 v[4:7], v[232:235], v[224:227], v[4:7]
	v_mfma_f32_16x16x32_bf16 v[0:3], v[240:243], v[224:227], v[0:3]
	v_mfma_f32_16x16x32_bf16 v[44:47], v[236:239], v[200:203], v[44:47]
	v_mfma_f32_16x16x32_bf16 v[40:43], v[244:247], v[200:203], v[40:43]
	v_mfma_f32_16x16x32_bf16 v[28:31], v[236:239], v[208:211], v[28:31]
	v_mfma_f32_16x16x32_bf16 v[24:27], v[244:247], v[208:211], v[24:27]
	v_mfma_f32_16x16x32_bf16 v[12:15], v[236:239], v[216:219], v[12:15]
	v_mfma_f32_16x16x32_bf16 v[8:11], v[244:247], v[216:219], v[8:11]
	v_mfma_f32_16x16x32_bf16 v[4:7], v[236:239], v[228:231], v[4:7]
	v_mfma_f32_16x16x32_bf16 v[0:3], v[244:247], v[228:231], v[0:3]
	s_setprio 0
	s_barrier
	ds_read_b128 v[160:163], v158
	ds_read_b128 v[184:187], v158 offset:1024
	ds_read_b128 v[188:191], v158 offset:2048
	ds_read_b128 v[192:195], v158 offset:3072
	s_add_u32 s54, s54, 0x80000
	s_addc_u32 s55, s55, 0
	s_mov_b32 m0, s58
	v_lshl_add_u64 v[232:233], s[54:55], 0, v[146:147]
	ds_read_b128 v[196:199], v156 offset:32768
	ds_read_b128 v[200:203], v156 offset:33792
	ds_read_b128 v[204:207], v156 offset:34816
	ds_read_b128 v[208:211], v156 offset:35840
	ds_read_b128 v[212:215], v156 offset:36864
	ds_read_b128 v[216:219], v156 offset:37888
	ds_read_b128 v[224:227], v156 offset:38912
	ds_read_b128 v[228:231], v156 offset:39936
	global_load_lds_dwordx4 v[232:233], off
	v_lshl_add_u64 v[232:233], s[54:55], 0, v[144:145]
	s_mov_b32 m0, s59
	s_nop 0
	global_load_lds_dwordx4 v[232:233], off
	s_waitcnt lgkmcnt(8)
	s_barrier
	s_waitcnt lgkmcnt(0)
	s_setprio 1
	s_waitcnt lgkmcnt(0)
	v_mfma_f32_16x16x32_bf16 v[124:127], v[160:163], v[196:199], v[124:127]
	v_mfma_f32_16x16x32_bf16 v[120:123], v[188:191], v[196:199], v[120:123]
	v_mfma_f32_16x16x32_bf16 v[116:119], v[160:163], v[204:207], v[116:119]
	v_mfma_f32_16x16x32_bf16 v[112:115], v[188:191], v[204:207], v[112:115]
	v_mfma_f32_16x16x32_bf16 v[100:103], v[160:163], v[212:215], v[100:103]
	v_mfma_f32_16x16x32_bf16 v[96:99], v[188:191], v[212:215], v[96:99]
	v_mfma_f32_16x16x32_bf16 v[84:87], v[160:163], v[224:227], v[84:87]
	v_mfma_f32_16x16x32_bf16 v[80:83], v[188:191], v[224:227], v[80:83]
	v_mfma_f32_16x16x32_bf16 v[124:127], v[184:187], v[200:203], v[124:127]
	v_mfma_f32_16x16x32_bf16 v[120:123], v[192:195], v[200:203], v[120:123]
	v_mfma_f32_16x16x32_bf16 v[116:119], v[184:187], v[208:211], v[116:119]
	v_mfma_f32_16x16x32_bf16 v[112:115], v[192:195], v[208:211], v[112:115]
	v_mfma_f32_16x16x32_bf16 v[100:103], v[184:187], v[216:219], v[100:103]
	v_mfma_f32_16x16x32_bf16 v[96:99], v[192:195], v[216:219], v[96:99]
	v_mfma_f32_16x16x32_bf16 v[84:87], v[184:187], v[228:231], v[84:87]
	v_mfma_f32_16x16x32_bf16 v[80:83], v[192:195], v[228:231], v[80:83]
	s_setprio 0
	s_barrier
	s_mov_b32 m0, s60
	v_add_u32_e32 v159, s64, v153
	v_lshl_add_u64 v[164:165], v[164:165], 0, s[34:35]
	ds_read_b128 v[232:235], v159
	ds_read_b128 v[236:239], v159 offset:1024
	ds_read_b128 v[240:243], v159 offset:2048
	ds_read_b128 v[244:247], v159 offset:3072
	global_load_lds_dwordx4 v[164:165], off
	v_lshl_add_u64 v[164:165], v[248:249], 0, s[34:35]
	s_mov_b32 m0, s61
	s_nop 0
	global_load_lds_dwordx4 v[164:165], off
	s_barrier
	s_waitcnt lgkmcnt(0)
	s_setprio 1
	s_waitcnt lgkmcnt(0)
	v_mfma_f32_16x16x32_bf16 v[108:111], v[232:235], v[196:199], v[108:111]
	v_mfma_f32_16x16x32_bf16 v[104:107], v[240:243], v[196:199], v[104:107]
	v_mfma_f32_16x16x32_bf16 v[92:95], v[232:235], v[204:207], v[92:95]
	v_mfma_f32_16x16x32_bf16 v[88:91], v[240:243], v[204:207], v[88:91]
	v_mfma_f32_16x16x32_bf16 v[76:79], v[232:235], v[212:215], v[76:79]
	v_mfma_f32_16x16x32_bf16 v[72:75], v[240:243], v[212:215], v[72:75]
	v_mfma_f32_16x16x32_bf16 v[68:71], v[232:235], v[224:227], v[68:71]
	v_mfma_f32_16x16x32_bf16 v[64:67], v[240:243], v[224:227], v[64:67]
	v_mfma_f32_16x16x32_bf16 v[108:111], v[236:239], v[200:203], v[108:111]
	v_mfma_f32_16x16x32_bf16 v[104:107], v[244:247], v[200:203], v[104:107]
	v_mfma_f32_16x16x32_bf16 v[92:95], v[236:239], v[208:211], v[92:95]
	v_mfma_f32_16x16x32_bf16 v[88:91], v[244:247], v[208:211], v[88:91]
	v_mfma_f32_16x16x32_bf16 v[76:79], v[236:239], v[216:219], v[76:79]
	v_mfma_f32_16x16x32_bf16 v[72:75], v[244:247], v[216:219], v[72:75]
	v_mfma_f32_16x16x32_bf16 v[68:71], v[236:239], v[228:231], v[68:71]
	v_mfma_f32_16x16x32_bf16 v[64:67], v[244:247], v[228:231], v[64:67]
	s_setprio 0
	s_mov_b32 m0, s62
	v_lshl_add_u64 v[164:165], v[250:251], 0, s[34:35]
	s_barrier
	ds_read_b128 v[196:199], v156 offset:49152
	ds_read_b128 v[200:203], v156 offset:50176
	ds_read_b128 v[204:207], v156 offset:51200
	ds_read_b128 v[208:211], v156 offset:52224
	ds_read_b128 v[212:215], v156 offset:53248
	ds_read_b128 v[216:219], v156 offset:54272
	ds_read_b128 v[224:227], v156 offset:55296
	ds_read_b128 v[228:231], v156 offset:56320
	global_load_lds_dwordx4 v[164:165], off
	v_lshl_add_u64 v[134:135], v[134:135], 0, s[34:35]
	s_mov_b32 m0, s63
	s_nop 0
	global_load_lds_dwordx4 v[134:135], off
	s_barrier
; #define PG8_STAGE(bufoff, gbase, voff) do { _Pragma("unroll") for (int _i = 0; _i < 2; ++_i) \
;         __builtin_amdgcn_global_load_lds((const unsigned*)((const char*)(gbase) + (voff)[_i]), (LAS unsigned*)(lds + (bufoff) + ldsw + _i * 8192), 16, 0, 0); } while (0)
; #define PG8_MMA(ai, bj, At, Bt) do { __builtin_amdgcn_s_setprio(1); _Pragma("unroll") for (int m = 0; m < 4; ++m) _Pragma("unroll") for (int n = 0; n < 2; ++n) _Pragma("unroll") for (int k = 0; k < 2; ++k) \
;         acc[ai][bj][m][n] = __builtin_amdgcn_mfma_f32_16x16x32_bf16(Bt[n][k], At[m][k], acc[ai][bj][m][n], 0, 0, 0); __builtin_amdgcn_s_setprio(0); } while (0)
; #define PG8_WAIT_V(n) asm volatile("s_waitcnt vmcnt(" #n ")" ::: "memory")
; #define PG8_WAIT_L(n) asm volatile("s_waitcnt lgkmcnt(" #n ")" ::: "memory")
; #define PG8_BAR __builtin_amdgcn_s_barrier()
; #define PG8_SCHED __builtin_amdgcn_sched_barrier(0)
; DI void gemm_phase(LAS unsigned char* lds, const Gemm g, const StaticOrder& S, const EpiBf16& E) {
;     ...
;         for (int t = 0; t < nt; t += 2) {
;     ...
;             PG8_BAR; PG8_WAIT_L(0); PG8_MMA(1, 0, At, B0); PG8_BAR; PG8_SCHED;
;             PG8_STAGE(PG8_SB(1, 1), b3 + hstep, voffB);
;             PG8_WAIT_V(6); PG8_BAR; PG8_MMA(1, 1, At, B1); PG8_BAR;
	s_waitcnt lgkmcnt(0)
	s_setprio 1
	s_waitcnt lgkmcnt(0)
	v_mfma_f32_16x16x32_bf16 v[60:63], v[160:163], v[196:199], v[60:63]
	v_mfma_f32_16x16x32_bf16 v[56:59], v[188:191], v[196:199], v[56:59]
	v_mfma_f32_16x16x32_bf16 v[52:55], v[160:163], v[204:207], v[52:55]
	v_mfma_f32_16x16x32_bf16 v[48:51], v[188:191], v[204:207], v[48:51]
	v_mfma_f32_16x16x32_bf16 v[36:39], v[160:163], v[212:215], v[36:39]
	v_mfma_f32_16x16x32_bf16 v[32:35], v[188:191], v[212:215], v[32:35]
	v_mfma_f32_16x16x32_bf16 v[20:23], v[160:163], v[224:227], v[20:23]
	v_mfma_f32_16x16x32_bf16 v[16:19], v[188:191], v[224:227], v[16:19]
	v_mfma_f32_16x16x32_bf16 v[60:63], v[184:187], v[200:203], v[60:63]
	v_mfma_f32_16x16x32_bf16 v[56:59], v[192:195], v[200:203], v[56:59]
	v_mfma_f32_16x16x32_bf16 v[52:55], v[184:187], v[208:211], v[52:55]
	v_mfma_f32_16x16x32_bf16 v[48:51], v[192:195], v[208:211], v[48:51]
	v_mfma_f32_16x16x32_bf16 v[36:39], v[184:187], v[216:219], v[36:39]
	v_mfma_f32_16x16x32_bf16 v[32:35], v[192:195], v[216:219], v[32:35]
	v_mfma_f32_16x16x32_bf16 v[20:23], v[184:187], v[228:231], v[20:23]
	v_mfma_f32_16x16x32_bf16 v[16:19], v[192:195], v[228:231], v[16:19]
	s_setprio 0
	s_barrier
	s_add_u32 s52, s52, 0x80080
	s_addc_u32 s53, s53, 0
	s_mov_b32 m0, s65
	v_lshl_add_u64 v[134:135], s[52:53], 0, v[132:133]
	global_load_lds_dwordx4 v[134:135], off
	v_lshl_add_u64 v[134:135], s[52:53], 0, v[142:143]
	s_mov_b32 m0, s66
	s_nop 0
	global_load_lds_dwordx4 v[134:135], off
	s_waitcnt vmcnt(6)
	s_barrier
	s_setprio 1
	v_mfma_f32_16x16x32_bf16 v[44:47], v[232:235], v[196:199], v[44:47]
	v_mfma_f32_16x16x32_bf16 v[40:43], v[240:243], v[196:199], v[40:43]
	v_mfma_f32_16x16x32_bf16 v[28:31], v[232:235], v[204:207], v[28:31]
	v_mfma_f32_16x16x32_bf16 v[24:27], v[240:243], v[204:207], v[24:27]
	v_mfma_f32_16x16x32_bf16 v[12:15], v[232:235], v[212:215], v[12:15]
	v_mfma_f32_16x16x32_bf16 v[8:11], v[240:243], v[212:215], v[8:11]
	v_mfma_f32_16x16x32_bf16 v[4:7], v[232:235], v[224:227], v[4:7]
	v_mfma_f32_16x16x32_bf16 v[0:3], v[240:243], v[224:227], v[0:3]
	v_mfma_f32_16x16x32_bf16 v[44:47], v[236:239], v[200:203], v[44:47]
	v_mfma_f32_16x16x32_bf16 v[40:43], v[244:247], v[200:203], v[40:43]
	v_mfma_f32_16x16x32_bf16 v[28:31], v[236:239], v[208:211], v[28:31]
	v_mfma_f32_16x16x32_bf16 v[24:27], v[244:247], v[208:211], v[24:27]
	v_mfma_f32_16x16x32_bf16 v[12:15], v[236:239], v[216:219], v[12:15]
	v_mfma_f32_16x16x32_bf16 v[8:11], v[244:247], v[216:219], v[8:11]
	v_mfma_f32_16x16x32_bf16 v[4:7], v[236:239], v[228:231], v[4:7]
	v_mfma_f32_16x16x32_bf16 v[0:3], v[244:247], v[228:231], v[0:3]
	s_setprio 0
	s_add_i32 s73, s73, 2
	s_add_u32 s50, s50, 0x100
	s_addc_u32 s51, s51, 0
	s_add_u32 s71, s71, 0x100
	s_addc_u32 s72, s72, 0
	s_cmp_gt_u32 s73, 29
	s_cbranch_scc0 .LBB0_181
	s_barrier
; #define PG8_WAIT_V(n) asm volatile("s_waitcnt vmcnt(" #n ")" ::: "memory")
; #define PG8_BAR __builtin_amdgcn_s_barrier()
;     DI void operator()(const f32x4 (&acc)[2][2][4][2], const Unit& u, int wr, int wc, int fr, int fq) const {
;         const int row0 = u.pm * BM + wr * 64 + fr; const int col0 = u.pn * BM + wc * 32 + 8 * fq;
; #pragma unroll
;         for (int ai = 0; ai < 2; ++ai)
; #pragma unroll
;             for (int m = 0; m < 4; ++m) { bf16_t* rowp = O + (size_t)(row0 + ai * HALF + m * 16) * ldc + col0;
; #pragma unroll
;                 for (int bj = 0; bj < 2; ++bj) { const f32x4 v0 = acc[ai][bj][m][0], v1 = acc[ai][bj][m][1];
;                     u32x4 w; w.x = pk2(v0[0], v0[1]); w.y = pk2(v0[2], v0[3]); w.z = pk2(v1[0], v1[1]); w.w = pk2(v1[2], v1[3]);
;                     *(u32x4*)(rowp + bj * HALF) = w; } }
;     }
; DI void gemm_phase(LAS unsigned char* lds, const Gemm g, const StaticOrder& S, const EpiBf16& E) {
;     ...
;         E(acc, cur, wr, wc, fr, fq);
;         if (!has_next) break;
; #pragma unroll
;         for (int a = 0; a < 2; ++a)
; #pragma unroll
;             for (int b = 0; b < 2; ++b)
; #pragma unroll
;                 for (int m = 0; m < 4; ++m)
; #pragma unroll
;                     for (int n = 0; n < 2; ++n) acc[a][b][m][n] = (f32x4){0.f, 0.f, 0.f, 0.f};
;         cur = nxt; cA = nA; cB = nB; ++ui;
;     }
;     PG8_WAIT_V(0);
;     if (wr == 0) PG8_BAR;
;     PG8_BAR;
	v_lshl_add_u32 v134, s40, 8, v152
	v_lshl_or_b32 v160, s68, 8, v154
	v_ashrrev_i32_e32 v161, 31, v160
	v_mov_b64_e32 v[162:163], s[38:39]
	s_movk_i32 s4, 0x3800
	v_cvt_pk_bf16_f32 v68, v68, v69
	v_cvt_pk_bf16_f32 v69, v70, v71
	v_cvt_pk_bf16_f32 v70, v64, v65
	v_add_u32_e32 v64, 0x80, v134
	v_mad_i64_i32 v[164:165], s[50:51], v134, s4, v[162:163]
	v_lshlrev_b64 v[160:161], 1, v[160:161]
	v_cvt_pk_bf16_f32 v108, v108, v109
	v_cvt_pk_bf16_f32 v109, v110, v111
	v_cvt_pk_bf16_f32 v110, v104, v105
	v_or_b32_e32 v104, 16, v134
	v_mad_i64_i32 v[64:65], s[50:51], v64, s4, v[162:163]
	v_cvt_pk_bf16_f32 v44, v44, v45
	v_cvt_pk_bf16_f32 v45, v46, v47
	v_cvt_pk_bf16_f32 v46, v40, v41
	v_add_u32_e32 v40, 0x90, v134
	v_lshl_add_u64 v[164:165], v[164:165], 0, v[160:161]
	v_cvt_pk_bf16_f32 v111, v106, v107
	v_mad_i64_i32 v[104:105], s[50:51], v104, s4, v[162:163]
	v_cvt_pk_bf16_f32 v92, v92, v93
	v_cvt_pk_bf16_f32 v93, v94, v95
	v_cvt_pk_bf16_f32 v94, v88, v89
	v_or_b32_e32 v88, 32, v134
	v_lshl_add_u64 v[64:65], v[64:65], 0, v[160:161]
	v_cvt_pk_bf16_f32 v47, v42, v43
	v_mad_i64_i32 v[40:41], s[50:51], v40, s4, v[162:163]
	v_cvt_pk_bf16_f32 v28, v28, v29
	v_cvt_pk_bf16_f32 v29, v30, v31
	v_cvt_pk_bf16_f32 v30, v24, v25
	v_add_u32_e32 v24, 0xa0, v134
	global_store_dwordx4 v[164:165], v[108:111], off offset:256 sc1
	v_cvt_pk_bf16_f32 v95, v90, v91
	v_mad_i64_i32 v[88:89], s[50:51], v88, s4, v[162:163]
	v_lshl_add_u64 v[108:109], v[104:105], 0, v[160:161]
	v_cvt_pk_bf16_f32 v76, v76, v77
	v_cvt_pk_bf16_f32 v77, v78, v79
	v_cvt_pk_bf16_f32 v78, v72, v73
	v_or_b32_e32 v72, 48, v134
	global_store_dwordx4 v[64:65], v[44:47], off offset:256 sc1
	v_cvt_pk_bf16_f32 v31, v26, v27
	v_mad_i64_i32 v[24:25], s[50:51], v24, s4, v[162:163]
	v_lshl_add_u64 v[44:45], v[40:41], 0, v[160:161]
	v_cvt_pk_bf16_f32 v12, v12, v13
	v_cvt_pk_bf16_f32 v13, v14, v15
	v_cvt_pk_bf16_f32 v14, v8, v9
	v_add_u32_e32 v8, 0xb0, v134
	global_store_dwordx4 v[108:109], v[92:95], off offset:256 sc1
	v_cvt_pk_bf16_f32 v79, v74, v75
	v_mad_i64_i32 v[72:73], s[50:51], v72, s4, v[162:163]
	v_lshl_add_u64 v[92:93], v[88:89], 0, v[160:161]
	global_store_dwordx4 v[44:45], v[28:31], off offset:256 sc1
	v_cvt_pk_bf16_f32 v15, v10, v11
	v_mad_i64_i32 v[8:9], s[50:51], v8, s4, v[162:163]
	v_lshl_add_u64 v[28:29], v[24:25], 0, v[160:161]
	v_cvt_pk_bf16_f32 v124, v124, v125
	v_cvt_pk_bf16_f32 v125, v126, v127
	v_cvt_pk_bf16_f32 v126, v120, v121
	v_cvt_pk_bf16_f32 v127, v122, v123
	v_cvt_pk_bf16_f32 v104, v116, v117
	v_cvt_pk_bf16_f32 v105, v118, v119
	v_cvt_pk_bf16_f32 v106, v112, v113
	v_cvt_pk_bf16_f32 v107, v114, v115
	v_cvt_pk_bf16_f32 v88, v100, v101
	v_cvt_pk_bf16_f32 v89, v102, v103
	v_cvt_pk_bf16_f32 v90, v96, v97
	v_cvt_pk_bf16_f32 v91, v98, v99
	global_store_dwordx4 v[92:93], v[76:79], off offset:256 sc1
	v_cvt_pk_bf16_f32 v74, v80, v81
	v_cvt_pk_bf16_f32 v75, v82, v83
	v_lshl_add_u64 v[76:77], v[72:73], 0, v[160:161]
	v_cvt_pk_bf16_f32 v72, v84, v85
	v_cvt_pk_bf16_f32 v73, v86, v87
	v_cvt_pk_bf16_f32 v71, v66, v67
	v_cvt_pk_bf16_f32 v60, v60, v61
	v_cvt_pk_bf16_f32 v61, v62, v63
	v_cvt_pk_bf16_f32 v62, v56, v57
	v_cvt_pk_bf16_f32 v63, v58, v59
	v_cvt_pk_bf16_f32 v40, v52, v53
	v_cvt_pk_bf16_f32 v41, v54, v55
	v_cvt_pk_bf16_f32 v42, v48, v49
	v_cvt_pk_bf16_f32 v43, v50, v51
	v_cvt_pk_bf16_f32 v24, v36, v37
	v_cvt_pk_bf16_f32 v25, v38, v39
	v_cvt_pk_bf16_f32 v26, v32, v33
	v_cvt_pk_bf16_f32 v27, v34, v35
	global_store_dwordx4 v[28:29], v[12:15], off offset:256 sc1
	v_cvt_pk_bf16_f32 v10, v16, v17
	v_cvt_pk_bf16_f32 v11, v18, v19
	v_lshl_add_u64 v[12:13], v[8:9], 0, v[160:161]
	v_cvt_pk_bf16_f32 v8, v20, v21
	v_cvt_pk_bf16_f32 v9, v22, v23
	v_cvt_pk_bf16_f32 v4, v4, v5
	v_cvt_pk_bf16_f32 v5, v6, v7
	v_cvt_pk_bf16_f32 v6, v0, v1
	v_cvt_pk_bf16_f32 v7, v2, v3
	s_and_b64 vcc, exec, s[0:1]
	s_mov_b32 s68, s42
	s_mov_b32 s40, s44
	s_mov_b64 s[52:53], s[48:49]
	s_mov_b64 s[50:51], s[46:47]
	global_store_dwordx4 v[164:165], v[124:127], off sc1
	global_store_dwordx4 v[108:109], v[104:107], off sc1
	global_store_dwordx4 v[92:93], v[88:91], off sc1
	global_store_dwordx4 v[76:77], v[72:75], off sc1
	global_store_dwordx4 v[76:77], v[68:71], off offset:256 sc1
	global_store_dwordx4 v[64:65], v[60:63], off sc1
	global_store_dwordx4 v[44:45], v[40:43], off sc1
	global_store_dwordx4 v[28:29], v[24:27], off sc1
	global_store_dwordx4 v[12:13], v[8:11], off sc1
	global_store_dwordx4 v[12:13], v[4:7], off offset:256 sc1
	s_cbranch_vccz .LBB0_178
	s_waitcnt vmcnt(0)
	s_cmpk_gt_u32 s3, 0xff
	s_cbranch_scc1 .LBB0_185
	s_barrier

; DI void gemm_phase(LAS unsigned char* lds, const Gemm g, const StaticOrder& S, const EpiBf16& E) {
;     ...
;         const bool has_next = S.next(ui + 1, nxt);
;         const char* nA = has_next ? (const char*)g.A + (size_t)nxt.pm * tstep : cA; const char* nB = has_next ? (const char*)g.Bt + (size_t)nxt.pn * tstep : cB;
;         for (int t = 0; t < nt; t += 2) {
;             const bool last = (t == nt - 2);
;             const char* a1 = cA + (size_t)(t + 1) * kstep;
;             const char* a2 = last ? nA : cA + (size_t)(t + 2) * kstep; const char* b2 = last ? nB : cB + (size_t)(t + 2) * kstep;
;             const char* a3 = a2 + kstep; const char* b3 = b2 + kstep;
;     ...
; #pragma unroll
;         for (int a = 0; a < 2; ++a)
; #pragma unroll
;             for (int b = 0; b < 2; ++b)
; #pragma unroll
;                 for (int m = 0; m < 4; ++m)
; #pragma unroll
;                     for (int n = 0; n < 2; ++n) acc[a][b][m][n] = (f32x4){0.f, 0.f, 0.f, 0.f};
;         cur = nxt; cA = nA; cB = nB; ++ui;
.LBB0_744:
	s_ashr_i32 s43, s42, 31
	s_lshl_b64 s[4:5], s[42:43], 20
	v_cmp_lt_i64_e32 vcc, s[44:45], v[140:141]
	s_add_u32 s44, s22, s4
	s_addc_u32 s45, s24, s5
	s_and_b64 s[4:5], vcc, exec
	s_cselect_b32 s43, s45, s49
	s_cselect_b32 s70, s44, s48
	s_ashr_i32 s41, s40, 31
	s_lshl_b64 s[4:5], s[40:41], 20
	s_add_u32 s46, s26, s4
	s_addc_u32 s47, s27, s5
	s_and_b64 s[4:5], vcc, exec
	s_cselect_b32 s41, s47, s51
	s_cselect_b32 s71, s46, s50
	s_add_u32 s48, s48, 0x80080
	s_addc_u32 s49, s49, 0
	s_add_u32 s72, s50, 0x100
	v_mov_b32_e32 v0, 0
	s_addc_u32 s73, s51, 0
	s_mov_b32 s74, -2
	v_mov_b32_e32 v1, v0
	v_mov_b32_e32 v2, v0
	v_mov_b32_e32 v3, v0
	v_mov_b32_e32 v4, v0
	v_mov_b32_e32 v5, v0
	v_mov_b32_e32 v6, v0
	v_mov_b32_e32 v7, v0
	v_mov_b32_e32 v8, v0
	v_mov_b32_e32 v9, v0
	v_mov_b32_e32 v10, v0
	v_mov_b32_e32 v11, v0
	v_mov_b32_e32 v12, v0
	v_mov_b32_e32 v13, v0
	v_mov_b32_e32 v14, v0
	v_mov_b32_e32 v15, v0
	v_mov_b32_e32 v24, v0
	v_mov_b32_e32 v25, v0
	v_mov_b32_e32 v26, v0
	v_mov_b32_e32 v27, v0
	v_mov_b32_e32 v28, v0
	v_mov_b32_e32 v29, v0
	v_mov_b32_e32 v30, v0
	v_mov_b32_e32 v31, v0
	v_mov_b32_e32 v40, v0
	v_mov_b32_e32 v41, v0
	v_mov_b32_e32 v42, v0
	v_mov_b32_e32 v43, v0
	v_mov_b32_e32 v44, v0
	v_mov_b32_e32 v45, v0
	v_mov_b32_e32 v46, v0
	v_mov_b32_e32 v47, v0
	v_mov_b32_e32 v16, v0
	v_mov_b32_e32 v17, v0
	v_mov_b32_e32 v18, v0
	v_mov_b32_e32 v19, v0
	v_mov_b32_e32 v20, v0
	v_mov_b32_e32 v21, v0
	v_mov_b32_e32 v22, v0
	v_mov_b32_e32 v23, v0
	v_mov_b32_e32 v32, v0
	v_mov_b32_e32 v33, v0
	v_mov_b32_e32 v34, v0
	v_mov_b32_e32 v35, v0
	v_mov_b32_e32 v36, v0
	v_mov_b32_e32 v37, v0
	v_mov_b32_e32 v38, v0
	v_mov_b32_e32 v39, v0
	v_mov_b32_e32 v48, v0
	v_mov_b32_e32 v49, v0
	v_mov_b32_e32 v50, v0
	v_mov_b32_e32 v51, v0
	v_mov_b32_e32 v52, v0
	v_mov_b32_e32 v53, v0
	v_mov_b32_e32 v54, v0
	v_mov_b32_e32 v55, v0
	v_mov_b32_e32 v56, v0
	v_mov_b32_e32 v57, v0
	v_mov_b32_e32 v58, v0
	v_mov_b32_e32 v59, v0
	v_mov_b32_e32 v60, v0
	v_mov_b32_e32 v61, v0
	v_mov_b32_e32 v62, v0
	v_mov_b32_e32 v63, v0
	v_mov_b32_e32 v64, v0
	v_mov_b32_e32 v65, v0
	v_mov_b32_e32 v66, v0
	v_mov_b32_e32 v67, v0
	v_mov_b32_e32 v68, v0
	v_mov_b32_e32 v69, v0
	v_mov_b32_e32 v70, v0
	v_mov_b32_e32 v71, v0
	v_mov_b32_e32 v72, v0
	v_mov_b32_e32 v73, v0
	v_mov_b32_e32 v74, v0
	v_mov_b32_e32 v75, v0
	v_mov_b32_e32 v76, v0
	v_mov_b32_e32 v77, v0
	v_mov_b32_e32 v78, v0
	v_mov_b32_e32 v79, v0
	v_mov_b32_e32 v88, v0
	v_mov_b32_e32 v89, v0
	v_mov_b32_e32 v90, v0
	v_mov_b32_e32 v91, v0
	v_mov_b32_e32 v92, v0
	v_mov_b32_e32 v93, v0
	v_mov_b32_e32 v94, v0
	v_mov_b32_e32 v95, v0
	v_mov_b32_e32 v104, v0
	v_mov_b32_e32 v105, v0
	v_mov_b32_e32 v106, v0
	v_mov_b32_e32 v107, v0
	v_mov_b32_e32 v108, v0
	v_mov_b32_e32 v109, v0
	v_mov_b32_e32 v110, v0
	v_mov_b32_e32 v111, v0
	v_mov_b32_e32 v80, v0
	v_mov_b32_e32 v81, v0
	v_mov_b32_e32 v82, v0
	v_mov_b32_e32 v83, v0
	v_mov_b32_e32 v84, v0
	v_mov_b32_e32 v85, v0
	v_mov_b32_e32 v86, v0
	v_mov_b32_e32 v87, v0
	v_mov_b32_e32 v96, v0
	v_mov_b32_e32 v97, v0
	v_mov_b32_e32 v98, v0
	v_mov_b32_e32 v99, v0
	v_mov_b32_e32 v100, v0
	v_mov_b32_e32 v101, v0
	v_mov_b32_e32 v102, v0
	v_mov_b32_e32 v103, v0
	v_mov_b32_e32 v112, v0
	v_mov_b32_e32 v113, v0
	v_mov_b32_e32 v114, v0
	v_mov_b32_e32 v115, v0
	v_mov_b32_e32 v116, v0
	v_mov_b32_e32 v117, v0
	v_mov_b32_e32 v118, v0
	v_mov_b32_e32 v119, v0
	v_mov_b32_e32 v120, v0
	v_mov_b32_e32 v121, v0
	v_mov_b32_e32 v122, v0
	v_mov_b32_e32 v123, v0
	v_mov_b32_e32 v124, v0
	v_mov_b32_e32 v125, v0
	v_mov_b32_e32 v126, v0
	v_mov_b32_e32 v127, v0
	s_branch .Lk745_first

; #define PG8_STAGE(bufoff, gbase, voff) do { _Pragma("unroll") for (int _i = 0; _i < 2; ++_i) \
;         __builtin_amdgcn_global_load_lds((const unsigned*)((const char*)(gbase) + (voff)[_i]), (LAS unsigned*)(lds + (bufoff) + ldsw + _i * 8192), 16, 0, 0); } while (0)
; #define PG8_LDA(dst, b, h) do { _Pragma("unroll") for (int m = 0; m < 4; ++m) _Pragma("unroll") for (int k = 0; k < 2; ++k) dst[m][k] = *(const LAS bf16x8*)(lds + PG8_SA(b, h) + aoff + m * 2048 + k * 1024); } while (0)
; #define PG8_LDB(dst, b, h) do { _Pragma("unroll") for (int n = 0; n < 2; ++n) _Pragma("unroll") for (int k = 0; k < 2; ++k) dst[n][k] = *(const LAS bf16x8*)(lds + PG8_SB(b, h) + boff + n * 2048 + k * 1024); } while (0)
; #define PG8_MMA(ai, bj, At, Bt) do { __builtin_amdgcn_s_setprio(1); _Pragma("unroll") for (int m = 0; m < 4; ++m) _Pragma("unroll") for (int n = 0; n < 2; ++n) _Pragma("unroll") for (int k = 0; k < 2; ++k) \
;         acc[ai][bj][m][n] = __builtin_amdgcn_mfma_f32_16x16x32_bf16(Bt[n][k], At[m][k], acc[ai][bj][m][n], 0, 0, 0); __builtin_amdgcn_s_setprio(0); } while (0)
; #define PG8_WAIT_L(n) asm volatile("s_waitcnt lgkmcnt(" #n ")" ::: "memory")
; #define PG8_BAR __builtin_amdgcn_s_barrier()
; #define PG8_SCHED __builtin_amdgcn_sched_barrier(0)
; DI void gemm_phase(LAS unsigned char* lds, const Gemm g, const StaticOrder& S, const EpiBf16& E) {
;     ...
;         for (int t = 0; t < nt; t += 2) {
;             const bool last = (t == nt - 2);
;             const char* a1 = cA + (size_t)(t + 1) * kstep;
;             const char* a2 = last ? nA : cA + (size_t)(t + 2) * kstep; const char* b2 = last ? nB : cB + (size_t)(t + 2) * kstep;
;             const char* a3 = a2 + kstep; const char* b3 = b2 + kstep;
;             PG8_LDB(B0, 0, 0); PG8_SCHED; PG8_LDA(At, 0, 0); PG8_STAGE(PG8_SA(1, 1), a1 + hstep, voffA);
;             PG8_WAIT_L(8); PG8_BAR; PG8_WAIT_L(0); PG8_MMA(0, 0, At, B0); PG8_BAR; PG8_SCHED;
;             PG8_LDB(B1, 0, 1); PG8_STAGE(PG8_SB(0, 0), b2, voffB);
;             PG8_BAR; PG8_WAIT_L(0); PG8_MMA(0, 1, At, B1); PG8_BAR;
;             PG8_LDA(At, 0, 1); PG8_STAGE(PG8_SA(0, 0), a2, voffA);
;             PG8_BAR; PG8_WAIT_L(0); PG8_MMA(1, 0, At, B0); PG8_BAR; PG8_SCHED;
.Lk745_first:
	v_add_u32_e32 v134, s28, v153
	ds_read_b128 v[156:159], v134
	ds_read_b128 v[160:163], v134 offset:1024
	ds_read_b128 v[184:187], v134 offset:2048
	ds_read_b128 v[188:191], v134 offset:3072
	s_add_u32 s4, s48, 0xfff80080
	s_addc_u32 s5, s49, -1
	s_cmp_eq_u32 s74, 28
	s_cselect_b32 s53, s43, s5
	s_cselect_b32 s52, s70, s4
	s_cselect_b32 s51, s41, s73
	s_cselect_b32 s50, s71, s72
	v_lshl_add_u64 v[134:135], s[48:49], 0, v[148:149]
	s_add_i32 m0, s39, 0xc000
	ds_read_b128 v[192:195], v155
	ds_read_b128 v[196:199], v155 offset:1024
	ds_read_b128 v[200:203], v155 offset:2048
	ds_read_b128 v[204:207], v155 offset:3072
	ds_read_b128 v[208:211], v155 offset:4096
	ds_read_b128 v[212:215], v155 offset:5120
	ds_read_b128 v[216:219], v155 offset:6144
	ds_read_b128 v[224:227], v155 offset:7168
	global_load_lds_dwordx4 v[134:135], off
	v_lshl_add_u64 v[134:135], s[48:49], 0, v[150:151]
	s_add_i32 m0, s39, 0xe000
	s_nop 0
	global_load_lds_dwordx4 v[134:135], off
	s_waitcnt lgkmcnt(8)
	s_barrier
	s_waitcnt lgkmcnt(0)
	s_setprio 1
	s_waitcnt lgkmcnt(0)
	v_mfma_f32_16x16x32_bf16 v[124:127], v[156:159], v[192:195], v[124:127]
	v_mfma_f32_16x16x32_bf16 v[120:123], v[184:187], v[192:195], v[120:123]
	v_mfma_f32_16x16x32_bf16 v[116:119], v[156:159], v[200:203], v[116:119]
	v_mfma_f32_16x16x32_bf16 v[112:115], v[184:187], v[200:203], v[112:115]
	v_mfma_f32_16x16x32_bf16 v[100:103], v[156:159], v[208:211], v[100:103]
	v_mfma_f32_16x16x32_bf16 v[96:99], v[184:187], v[208:211], v[96:99]
	v_mfma_f32_16x16x32_bf16 v[84:87], v[156:159], v[216:219], v[84:87]
	v_mfma_f32_16x16x32_bf16 v[80:83], v[184:187], v[216:219], v[80:83]
	v_mfma_f32_16x16x32_bf16 v[124:127], v[160:163], v[196:199], v[124:127]
	v_mfma_f32_16x16x32_bf16 v[120:123], v[188:191], v[196:199], v[120:123]
	v_mfma_f32_16x16x32_bf16 v[116:119], v[160:163], v[204:207], v[116:119]
	v_mfma_f32_16x16x32_bf16 v[112:115], v[188:191], v[204:207], v[112:115]
	v_mfma_f32_16x16x32_bf16 v[100:103], v[160:163], v[212:215], v[100:103]
	v_mfma_f32_16x16x32_bf16 v[96:99], v[188:191], v[212:215], v[96:99]
	v_mfma_f32_16x16x32_bf16 v[84:87], v[160:163], v[224:227], v[84:87]
	v_mfma_f32_16x16x32_bf16 v[80:83], v[188:191], v[224:227], v[80:83]
	s_setprio 0
	s_barrier
	v_add_u32_e32 v134, s55, v153
	s_mov_b32 m0, s30
	ds_read_b128 v[228:231], v134
	ds_read_b128 v[232:235], v134 offset:1024
	ds_read_b128 v[236:239], v134 offset:2048
	ds_read_b128 v[240:243], v134 offset:3072
	v_lshl_add_u64 v[134:135], s[50:51], 0, v[132:133]
	global_load_lds_dwordx4 v[134:135], off
	v_lshl_add_u64 v[164:165], s[50:51], 0, v[146:147]
	s_mov_b32 m0, s31
	s_nop 0
	global_load_lds_dwordx4 v[164:165], off
	s_barrier
	s_waitcnt lgkmcnt(0)
	s_setprio 1
	s_waitcnt lgkmcnt(0)
	v_mfma_f32_16x16x32_bf16 v[108:111], v[228:231], v[192:195], v[108:111]
	v_mfma_f32_16x16x32_bf16 v[104:107], v[236:239], v[192:195], v[104:107]
	v_mfma_f32_16x16x32_bf16 v[92:95], v[228:231], v[200:203], v[92:95]
	v_mfma_f32_16x16x32_bf16 v[88:91], v[236:239], v[200:203], v[88:91]
	v_mfma_f32_16x16x32_bf16 v[76:79], v[228:231], v[208:211], v[76:79]
	v_mfma_f32_16x16x32_bf16 v[72:75], v[236:239], v[208:211], v[72:75]
	v_mfma_f32_16x16x32_bf16 v[68:71], v[228:231], v[216:219], v[68:71]
	v_mfma_f32_16x16x32_bf16 v[64:67], v[236:239], v[216:219], v[64:67]
	v_mfma_f32_16x16x32_bf16 v[108:111], v[232:235], v[196:199], v[108:111]
	v_mfma_f32_16x16x32_bf16 v[104:107], v[240:243], v[196:199], v[104:107]
	v_mfma_f32_16x16x32_bf16 v[92:95], v[232:235], v[204:207], v[92:95]
	v_mfma_f32_16x16x32_bf16 v[88:91], v[240:243], v[204:207], v[88:91]
	v_mfma_f32_16x16x32_bf16 v[76:79], v[232:235], v[212:215], v[76:79]
	v_mfma_f32_16x16x32_bf16 v[72:75], v[240:243], v[212:215], v[72:75]
	v_mfma_f32_16x16x32_bf16 v[68:71], v[232:235], v[224:227], v[68:71]
	v_mfma_f32_16x16x32_bf16 v[64:67], v[240:243], v[224:227], v[64:67]
	s_setprio 0
	s_mov_b32 m0, s39
	v_lshl_add_u64 v[244:245], s[52:53], 0, v[142:143]
	s_barrier
	ds_read_b128 v[192:195], v155 offset:16384
	ds_read_b128 v[196:199], v155 offset:17408
	ds_read_b128 v[200:203], v155 offset:18432
	ds_read_b128 v[204:207], v155 offset:19456
	ds_read_b128 v[208:211], v155 offset:20480
	ds_read_b128 v[212:215], v155 offset:21504
	ds_read_b128 v[216:219], v155 offset:22528
	ds_read_b128 v[224:227], v155 offset:23552
	global_load_lds_dwordx4 v[244:245], off
	v_lshl_add_u64 v[246:247], s[52:53], 0, v[144:145]
	s_mov_b32 m0, s54
	s_nop 0
	global_load_lds_dwordx4 v[246:247], off
	s_barrier
	s_waitcnt lgkmcnt(0)
	s_setprio 1
	s_waitcnt lgkmcnt(0)
	v_mfma_f32_16x16x32_bf16 v[60:63], v[156:159], v[192:195], v[60:63]
	v_mfma_f32_16x16x32_bf16 v[56:59], v[184:187], v[192:195], v[56:59]
	v_mfma_f32_16x16x32_bf16 v[52:55], v[156:159], v[200:203], v[52:55]
	v_mfma_f32_16x16x32_bf16 v[48:51], v[184:187], v[200:203], v[48:51]
	v_mfma_f32_16x16x32_bf16 v[36:39], v[156:159], v[208:211], v[36:39]
	v_mfma_f32_16x16x32_bf16 v[32:35], v[184:187], v[208:211], v[32:35]
	v_mfma_f32_16x16x32_bf16 v[20:23], v[156:159], v[216:219], v[20:23]
	v_mfma_f32_16x16x32_bf16 v[16:19], v[184:187], v[216:219], v[16:19]
	v_mfma_f32_16x16x32_bf16 v[60:63], v[160:163], v[196:199], v[60:63]
	v_mfma_f32_16x16x32_bf16 v[56:59], v[188:191], v[196:199], v[56:59]
	v_mfma_f32_16x16x32_bf16 v[52:55], v[160:163], v[204:207], v[52:55]
	v_mfma_f32_16x16x32_bf16 v[48:51], v[188:191], v[204:207], v[48:51]
	v_mfma_f32_16x16x32_bf16 v[36:39], v[160:163], v[212:215], v[36:39]
	v_mfma_f32_16x16x32_bf16 v[32:35], v[188:191], v[212:215], v[32:35]
	v_mfma_f32_16x16x32_bf16 v[20:23], v[160:163], v[224:227], v[20:23]
	v_mfma_f32_16x16x32_bf16 v[16:19], v[188:191], v[224:227], v[16:19]
	s_setprio 0
	s_barrier
; #define PG8_STAGE(bufoff, gbase, voff) do { _Pragma("unroll") for (int _i = 0; _i < 2; ++_i) \
;         __builtin_amdgcn_global_load_lds((const unsigned*)((const char*)(gbase) + (voff)[_i]), (LAS unsigned*)(lds + (bufoff) + ldsw + _i * 8192), 16, 0, 0); } while (0)
; #define PG8_LDA(dst, b, h) do { _Pragma("unroll") for (int m = 0; m < 4; ++m) _Pragma("unroll") for (int k = 0; k < 2; ++k) dst[m][k] = *(const LAS bf16x8*)(lds + PG8_SA(b, h) + aoff + m * 2048 + k * 1024); } while (0)
; #define PG8_LDB(dst, b, h) do { _Pragma("unroll") for (int n = 0; n < 2; ++n) _Pragma("unroll") for (int k = 0; k < 2; ++k) dst[n][k] = *(const LAS bf16x8*)(lds + PG8_SB(b, h) + boff + n * 2048 + k * 1024); } while (0)
; #define PG8_MMA(ai, bj, At, Bt) do { __builtin_amdgcn_s_setprio(1); _Pragma("unroll") for (int m = 0; m < 4; ++m) _Pragma("unroll") for (int n = 0; n < 2; ++n) _Pragma("unroll") for (int k = 0; k < 2; ++k) \
;         acc[ai][bj][m][n] = __builtin_amdgcn_mfma_f32_16x16x32_bf16(Bt[n][k], At[m][k], acc[ai][bj][m][n], 0, 0, 0); __builtin_amdgcn_s_setprio(0); } while (0)
; #define PG8_WAIT_V(n) asm volatile("s_waitcnt vmcnt(" #n ")" ::: "memory")
; #define PG8_WAIT_L(n) asm volatile("s_waitcnt lgkmcnt(" #n ")" ::: "memory")
; #define PG8_BAR __builtin_amdgcn_s_barrier()
; #define PG8_SCHED __builtin_amdgcn_sched_barrier(0)
; DI void gemm_phase(LAS unsigned char* lds, const Gemm g, const StaticOrder& S, const EpiBf16& E) {
;     ...
;             PG8_STAGE(PG8_SB(0, 1), b2 + hstep, voffB);
;             PG8_WAIT_V(6); PG8_BAR; PG8_MMA(1, 1, At, B1); PG8_BAR;
;             PG8_LDB(B0, 1, 0); PG8_SCHED; PG8_LDA(At, 1, 0); PG8_STAGE(PG8_SA(0, 1), a2 + hstep, voffA);
;             PG8_WAIT_L(8); PG8_BAR; PG8_WAIT_L(0); PG8_MMA(0, 0, At, B0); PG8_BAR; PG8_SCHED;
;             PG8_LDB(B1, 1, 1); PG8_STAGE(PG8_SB(1, 0), b3, voffB);
;             PG8_BAR; PG8_WAIT_L(0); PG8_MMA(0, 1, At, B1); PG8_BAR;
;             PG8_LDA(At, 1, 1); PG8_STAGE(PG8_SA(1, 0), a3, voffA);
;             PG8_BAR; PG8_WAIT_L(0); PG8_MMA(1, 0, At, B0); PG8_BAR; PG8_SCHED;
;             PG8_STAGE(PG8_SB(1, 1), b3 + hstep, voffB);
	s_add_u32 s4, s50, 0x80000
	s_addc_u32 s5, s51, 0
	s_mov_b32 m0, s56
	v_lshl_add_u64 v[156:157], s[4:5], 0, v[132:133]
	global_load_lds_dwordx4 v[156:157], off
	v_lshl_add_u64 v[156:157], s[4:5], 0, v[146:147]
	s_mov_b32 m0, s57
	s_nop 0
	global_load_lds_dwordx4 v[156:157], off
	s_waitcnt vmcnt(6)
	s_barrier
	s_setprio 1
	v_mfma_f32_16x16x32_bf16 v[44:47], v[228:231], v[192:195], v[44:47]
	v_mfma_f32_16x16x32_bf16 v[40:43], v[236:239], v[192:195], v[40:43]
	v_mfma_f32_16x16x32_bf16 v[28:31], v[228:231], v[200:203], v[28:31]
	v_mfma_f32_16x16x32_bf16 v[24:27], v[236:239], v[200:203], v[24:27]
	v_mfma_f32_16x16x32_bf16 v[12:15], v[228:231], v[208:211], v[12:15]
	v_mfma_f32_16x16x32_bf16 v[8:11], v[236:239], v[208:211], v[8:11]
	v_mfma_f32_16x16x32_bf16 v[4:7], v[228:231], v[216:219], v[4:7]
	v_mfma_f32_16x16x32_bf16 v[0:3], v[236:239], v[216:219], v[0:3]
	v_mfma_f32_16x16x32_bf16 v[44:47], v[232:235], v[196:199], v[44:47]
	v_mfma_f32_16x16x32_bf16 v[40:43], v[240:243], v[196:199], v[40:43]
	v_mfma_f32_16x16x32_bf16 v[28:31], v[232:235], v[204:207], v[28:31]
	v_mfma_f32_16x16x32_bf16 v[24:27], v[240:243], v[204:207], v[24:27]
	v_mfma_f32_16x16x32_bf16 v[12:15], v[232:235], v[212:215], v[12:15]
	v_mfma_f32_16x16x32_bf16 v[8:11], v[240:243], v[212:215], v[8:11]
	v_mfma_f32_16x16x32_bf16 v[4:7], v[232:235], v[224:227], v[4:7]
	v_mfma_f32_16x16x32_bf16 v[0:3], v[240:243], v[224:227], v[0:3]
	s_setprio 0
	v_add_u32_e32 v183, s60, v153
	s_barrier
	ds_read_b128 v[156:159], v183
	ds_read_b128 v[160:163], v183 offset:1024
	ds_read_b128 v[184:187], v183 offset:2048
	ds_read_b128 v[188:191], v183 offset:3072
	s_add_u32 s4, s52, 0x80000
	s_addc_u32 s5, s53, 0
	s_mov_b32 m0, s58
	v_lshl_add_u64 v[228:229], s[4:5], 0, v[142:143]
	ds_read_b128 v[192:195], v155 offset:32768
	ds_read_b128 v[196:199], v155 offset:33792
	ds_read_b128 v[200:203], v155 offset:34816
	ds_read_b128 v[204:207], v155 offset:35840
	ds_read_b128 v[208:211], v155 offset:36864
	ds_read_b128 v[212:215], v155 offset:37888
	ds_read_b128 v[216:219], v155 offset:38912
	ds_read_b128 v[224:227], v155 offset:39936
	global_load_lds_dwordx4 v[228:229], off
	v_lshl_add_u64 v[228:229], s[4:5], 0, v[144:145]
	s_mov_b32 m0, s59
	s_nop 0
	global_load_lds_dwordx4 v[228:229], off
	s_waitcnt lgkmcnt(8)
	s_barrier
	s_waitcnt lgkmcnt(0)
	s_setprio 1
	s_waitcnt lgkmcnt(0)
	v_mfma_f32_16x16x32_bf16 v[124:127], v[156:159], v[192:195], v[124:127]
	v_mfma_f32_16x16x32_bf16 v[120:123], v[184:187], v[192:195], v[120:123]
	v_mfma_f32_16x16x32_bf16 v[116:119], v[156:159], v[200:203], v[116:119]
	v_mfma_f32_16x16x32_bf16 v[112:115], v[184:187], v[200:203], v[112:115]
	v_mfma_f32_16x16x32_bf16 v[100:103], v[156:159], v[208:211], v[100:103]
	v_mfma_f32_16x16x32_bf16 v[96:99], v[184:187], v[208:211], v[96:99]
	v_mfma_f32_16x16x32_bf16 v[84:87], v[156:159], v[216:219], v[84:87]
	v_mfma_f32_16x16x32_bf16 v[80:83], v[184:187], v[216:219], v[80:83]
	v_mfma_f32_16x16x32_bf16 v[124:127], v[160:163], v[196:199], v[124:127]
	v_mfma_f32_16x16x32_bf16 v[120:123], v[188:191], v[196:199], v[120:123]
	v_mfma_f32_16x16x32_bf16 v[116:119], v[160:163], v[204:207], v[116:119]
	v_mfma_f32_16x16x32_bf16 v[112:115], v[188:191], v[204:207], v[112:115]
	v_mfma_f32_16x16x32_bf16 v[100:103], v[160:163], v[212:215], v[100:103]
	v_mfma_f32_16x16x32_bf16 v[96:99], v[188:191], v[212:215], v[96:99]
	v_mfma_f32_16x16x32_bf16 v[84:87], v[160:163], v[224:227], v[84:87]
	v_mfma_f32_16x16x32_bf16 v[80:83], v[188:191], v[224:227], v[80:83]
	s_setprio 0
	s_barrier
	s_mov_b32 m0, s61
	v_add_u32_e32 v183, s65, v153
	v_lshl_add_u64 v[134:135], v[134:135], 0, s[34:35]
	ds_read_b128 v[228:231], v183
	ds_read_b128 v[232:235], v183 offset:1024
	ds_read_b128 v[236:239], v183 offset:2048
	ds_read_b128 v[240:243], v183 offset:3072
	global_load_lds_dwordx4 v[134:135], off
	v_lshl_add_u64 v[134:135], v[164:165], 0, s[34:35]
	s_mov_b32 m0, s62
	s_nop 0
	global_load_lds_dwordx4 v[134:135], off
	s_barrier
	s_waitcnt lgkmcnt(0)
	s_setprio 1
	s_waitcnt lgkmcnt(0)
	v_mfma_f32_16x16x32_bf16 v[108:111], v[228:231], v[192:195], v[108:111]
	v_mfma_f32_16x16x32_bf16 v[104:107], v[236:239], v[192:195], v[104:107]
	v_mfma_f32_16x16x32_bf16 v[92:95], v[228:231], v[200:203], v[92:95]
	v_mfma_f32_16x16x32_bf16 v[88:91], v[236:239], v[200:203], v[88:91]
	v_mfma_f32_16x16x32_bf16 v[76:79], v[228:231], v[208:211], v[76:79]
	v_mfma_f32_16x16x32_bf16 v[72:75], v[236:239], v[208:211], v[72:75]
	v_mfma_f32_16x16x32_bf16 v[68:71], v[228:231], v[216:219], v[68:71]
	v_mfma_f32_16x16x32_bf16 v[64:67], v[236:239], v[216:219], v[64:67]
	v_mfma_f32_16x16x32_bf16 v[108:111], v[232:235], v[196:199], v[108:111]
	v_mfma_f32_16x16x32_bf16 v[104:107], v[240:243], v[196:199], v[104:107]
	v_mfma_f32_16x16x32_bf16 v[92:95], v[232:235], v[204:207], v[92:95]
	v_mfma_f32_16x16x32_bf16 v[88:91], v[240:243], v[204:207], v[88:91]
	v_mfma_f32_16x16x32_bf16 v[76:79], v[232:235], v[212:215], v[76:79]
	v_mfma_f32_16x16x32_bf16 v[72:75], v[240:243], v[212:215], v[72:75]
	v_mfma_f32_16x16x32_bf16 v[68:71], v[232:235], v[224:227], v[68:71]
	v_mfma_f32_16x16x32_bf16 v[64:67], v[240:243], v[224:227], v[64:67]
	s_setprio 0
	s_mov_b32 m0, s63
	v_lshl_add_u64 v[134:135], v[244:245], 0, s[34:35]
	s_barrier
	ds_read_b128 v[192:195], v155 offset:49152
	ds_read_b128 v[196:199], v155 offset:50176
	ds_read_b128 v[200:203], v155 offset:51200
	ds_read_b128 v[204:207], v155 offset:52224
	ds_read_b128 v[208:211], v155 offset:53248
	ds_read_b128 v[212:215], v155 offset:54272
	ds_read_b128 v[216:219], v155 offset:55296
	ds_read_b128 v[224:227], v155 offset:56320
	global_load_lds_dwordx4 v[134:135], off
	v_lshl_add_u64 v[134:135], v[246:247], 0, s[34:35]
	s_mov_b32 m0, s64
	s_nop 0
	global_load_lds_dwordx4 v[134:135], off
	s_barrier
; #define PG8_STAGE(bufoff, gbase, voff) do { _Pragma("unroll") for (int _i = 0; _i < 2; ++_i) \
;         __builtin_amdgcn_global_load_lds((const unsigned*)((const char*)(gbase) + (voff)[_i]), (LAS unsigned*)(lds + (bufoff) + ldsw + _i * 8192), 16, 0, 0); } while (0)
; #define PG8_MMA(ai, bj, At, Bt) do { __builtin_amdgcn_s_setprio(1); _Pragma("unroll") for (int m = 0; m < 4; ++m) _Pragma("unroll") for (int n = 0; n < 2; ++n) _Pragma("unroll") for (int k = 0; k < 2; ++k) \
;         acc[ai][bj][m][n] = __builtin_amdgcn_mfma_f32_16x16x32_bf16(Bt[n][k], At[m][k], acc[ai][bj][m][n], 0, 0, 0); __builtin_amdgcn_s_setprio(0); } while (0)
; #define PG8_WAIT_V(n) asm volatile("s_waitcnt vmcnt(" #n ")" ::: "memory")
; #define PG8_WAIT_L(n) asm volatile("s_waitcnt lgkmcnt(" #n ")" ::: "memory")
; #define PG8_BAR __builtin_amdgcn_s_barrier()
; #define PG8_SCHED __builtin_amdgcn_sched_barrier(0)
; DI void gemm_phase(LAS unsigned char* lds, const Gemm g, const StaticOrder& S, const EpiBf16& E) {
;     ...
;         for (int t = 0; t < nt; t += 2) {
;     ...
;             PG8_BAR; PG8_WAIT_L(0); PG8_MMA(1, 0, At, B0); PG8_BAR; PG8_SCHED;
;             PG8_STAGE(PG8_SB(1, 1), b3 + hstep, voffB);
;             PG8_WAIT_V(6); PG8_BAR; PG8_MMA(1, 1, At, B1); PG8_BAR;
	s_waitcnt lgkmcnt(0)
	s_setprio 1
	s_waitcnt lgkmcnt(0)
	v_mfma_f32_16x16x32_bf16 v[60:63], v[156:159], v[192:195], v[60:63]
	v_mfma_f32_16x16x32_bf16 v[56:59], v[184:187], v[192:195], v[56:59]
	v_mfma_f32_16x16x32_bf16 v[52:55], v[156:159], v[200:203], v[52:55]
	v_mfma_f32_16x16x32_bf16 v[48:51], v[184:187], v[200:203], v[48:51]
	v_mfma_f32_16x16x32_bf16 v[36:39], v[156:159], v[208:211], v[36:39]
	v_mfma_f32_16x16x32_bf16 v[32:35], v[184:187], v[208:211], v[32:35]
	v_mfma_f32_16x16x32_bf16 v[20:23], v[156:159], v[216:219], v[20:23]
	v_mfma_f32_16x16x32_bf16 v[16:19], v[184:187], v[216:219], v[16:19]
	v_mfma_f32_16x16x32_bf16 v[60:63], v[160:163], v[196:199], v[60:63]
	v_mfma_f32_16x16x32_bf16 v[56:59], v[188:191], v[196:199], v[56:59]
	v_mfma_f32_16x16x32_bf16 v[52:55], v[160:163], v[204:207], v[52:55]
	v_mfma_f32_16x16x32_bf16 v[48:51], v[188:191], v[204:207], v[48:51]
	v_mfma_f32_16x16x32_bf16 v[36:39], v[160:163], v[212:215], v[36:39]
	v_mfma_f32_16x16x32_bf16 v[32:35], v[188:191], v[212:215], v[32:35]
	v_mfma_f32_16x16x32_bf16 v[20:23], v[160:163], v[224:227], v[20:23]
	v_mfma_f32_16x16x32_bf16 v[16:19], v[188:191], v[224:227], v[16:19]
	s_setprio 0
	s_barrier
	s_add_u32 s4, s50, 0x80080
	s_addc_u32 s5, s51, 0
	s_mov_b32 m0, s66
	v_lshl_add_u64 v[134:135], s[4:5], 0, v[132:133]
	global_load_lds_dwordx4 v[134:135], off
	v_lshl_add_u64 v[134:135], s[4:5], 0, v[146:147]
	s_mov_b32 m0, s67
	s_nop 0
	global_load_lds_dwordx4 v[134:135], off
	s_waitcnt vmcnt(6)
	s_barrier
	s_setprio 1
	v_mfma_f32_16x16x32_bf16 v[44:47], v[228:231], v[192:195], v[44:47]
	v_mfma_f32_16x16x32_bf16 v[40:43], v[236:239], v[192:195], v[40:43]
	v_mfma_f32_16x16x32_bf16 v[28:31], v[228:231], v[200:203], v[28:31]
	v_mfma_f32_16x16x32_bf16 v[24:27], v[236:239], v[200:203], v[24:27]
	v_mfma_f32_16x16x32_bf16 v[12:15], v[228:231], v[208:211], v[12:15]
	v_mfma_f32_16x16x32_bf16 v[8:11], v[236:239], v[208:211], v[8:11]
	v_mfma_f32_16x16x32_bf16 v[4:7], v[228:231], v[216:219], v[4:7]
	v_mfma_f32_16x16x32_bf16 v[0:3], v[236:239], v[216:219], v[0:3]
	v_mfma_f32_16x16x32_bf16 v[44:47], v[232:235], v[196:199], v[44:47]
	v_mfma_f32_16x16x32_bf16 v[40:43], v[240:243], v[196:199], v[40:43]
	v_mfma_f32_16x16x32_bf16 v[28:31], v[232:235], v[204:207], v[28:31]
	v_mfma_f32_16x16x32_bf16 v[24:27], v[240:243], v[204:207], v[24:27]
	v_mfma_f32_16x16x32_bf16 v[12:15], v[232:235], v[212:215], v[12:15]
	v_mfma_f32_16x16x32_bf16 v[8:11], v[240:243], v[212:215], v[8:11]
	v_mfma_f32_16x16x32_bf16 v[4:7], v[232:235], v[224:227], v[4:7]
	v_mfma_f32_16x16x32_bf16 v[0:3], v[240:243], v[224:227], v[0:3]
	s_setprio 0
	s_add_i32 s74, s74, 2
	s_add_u32 s48, s48, 0x100
	s_addc_u32 s49, s49, 0
	s_add_u32 s72, s72, 0x100
	s_addc_u32 s73, s73, 0
	s_cmp_gt_u32 s74, 29
	s_cbranch_scc0 .LBB0_745
	s_barrier
; #define PG8_WAIT_V(n) asm volatile("s_waitcnt vmcnt(" #n ")" ::: "memory")
; #define PG8_BAR __builtin_amdgcn_s_barrier()
;     DI void operator()(const f32x4 (&acc)[2][2][4][2], const Unit& u, int wr, int wc, int fr, int fq) const {
;         const int row0 = u.pm * BM + wr * 64 + fr; const int col0 = u.pn * BM + wc * 32 + 8 * fq;
; #pragma unroll
;         for (int ai = 0; ai < 2; ++ai)
; #pragma unroll
;             for (int m = 0; m < 4; ++m) { bf16_t* rowp = O + (size_t)(row0 + ai * HALF + m * 16) * ldc + col0;
; #pragma unroll
;                 for (int bj = 0; bj < 2; ++bj) { const f32x4 v0 = acc[ai][bj][m][0], v1 = acc[ai][bj][m][1];
;                     u32x4 w; w.x = pk2(v0[0], v0[1]); w.y = pk2(v0[2], v0[3]); w.z = pk2(v1[0], v1[1]); w.w = pk2(v1[2], v1[3]);
;                     *(u32x4*)(rowp + bj * HALF) = w; } }
;     }
; DI void gemm_phase(LAS unsigned char* lds, const Gemm g, const StaticOrder& S, const EpiBf16& E) {
;     ...
;         E(acc, cur, wr, wc, fr, fq);
;         if (!has_next) break;
; #pragma unroll
;         for (int a = 0; a < 2; ++a)
; #pragma unroll
;             for (int b = 0; b < 2; ++b)
; #pragma unroll
;                 for (int m = 0; m < 4; ++m)
; #pragma unroll
;                     for (int n = 0; n < 2; ++n) acc[a][b][m][n] = (f32x4){0.f, 0.f, 0.f, 0.f};
;         cur = nxt; cA = nA; cB = nB; ++ui;
;     }
;     PG8_WAIT_V(0);
;     if (wr == 0) PG8_BAR;
;     PG8_BAR;
	v_lshl_add_u32 v134, s38, 8, v152
	v_lshl_or_b32 v156, s69, 8, v154
	v_ashrrev_i32_e32 v135, 31, v134
	v_ashrrev_i32_e32 v157, 31, v156
	v_lshlrev_b64 v[158:159], 12, v[134:135]
	v_lshl_add_u64 v[158:159], s[36:37], 0, v[158:159]
	v_lshlrev_b64 v[156:157], 1, v[156:157]
	v_lshl_add_u64 v[158:159], v[158:159], 0, v[156:157]
	s_mov_b64 s[4:5], 0x80000
	v_cvt_pk_bf16_f32 v68, v68, v69
	v_cvt_pk_bf16_f32 v69, v70, v71
	v_cvt_pk_bf16_f32 v70, v64, v65
	v_lshl_add_u64 v[64:65], v[158:159], 0, s[4:5]
	s_mov_b32 s4, 0x80000
	v_cvt_pk_bf16_f32 v60, v60, v61
	v_cvt_pk_bf16_f32 v61, v62, v63
	v_cvt_pk_bf16_f32 v62, v56, v57
	v_add_co_u32_e32 v56, vcc, s4, v158
	v_cvt_pk_bf16_f32 v44, v44, v45
	v_cvt_pk_bf16_f32 v45, v46, v47
	v_cvt_pk_bf16_f32 v46, v40, v41
	v_cvt_pk_bf16_f32 v47, v42, v43
	s_mov_b64 s[4:5], 0x90000
	v_addc_co_u32_e32 v57, vcc, 0, v159, vcc
	global_store_dwordx4 v[64:65], v[44:47], off offset:256 sc1
	v_cvt_pk_bf16_f32 v108, v108, v109
	v_cvt_pk_bf16_f32 v109, v110, v111
	v_lshl_add_u64 v[44:45], v[158:159], 0, s[4:5]
	s_mov_b32 s4, 0x90000
	v_cvt_pk_bf16_f32 v110, v104, v105
	v_or_b32_e32 v104, 16, v134
	v_add_co_u32_e32 v46, vcc, s4, v158
	v_cvt_pk_bf16_f32 v28, v28, v29
	v_cvt_pk_bf16_f32 v29, v30, v31
	v_cvt_pk_bf16_f32 v30, v24, v25
	v_cvt_pk_bf16_f32 v31, v26, v27
	s_mov_b64 s[4:5], 0xa0000
	v_ashrrev_i32_e32 v105, 31, v104
	v_cvt_pk_bf16_f32 v92, v92, v93
	v_cvt_pk_bf16_f32 v93, v94, v95
	v_cvt_pk_bf16_f32 v94, v88, v89
	v_or_b32_e32 v88, 32, v134
	v_addc_co_u32_e32 v47, vcc, 0, v159, vcc
	global_store_dwordx4 v[44:45], v[28:31], off offset:256 sc1
	v_lshlrev_b64 v[104:105], 12, v[104:105]
	v_ashrrev_i32_e32 v89, 31, v88
	v_lshl_add_u64 v[28:29], v[158:159], 0, s[4:5]
	s_mov_b32 s4, 0xa0000
	v_cvt_pk_bf16_f32 v76, v76, v77
	v_cvt_pk_bf16_f32 v77, v78, v79
	v_cvt_pk_bf16_f32 v78, v72, v73
	v_or_b32_e32 v72, 48, v134
	v_add_co_u32_e32 v30, vcc, s4, v158
	v_cvt_pk_bf16_f32 v111, v106, v107
	v_lshl_add_u64 v[104:105], s[36:37], 0, v[104:105]
	v_lshlrev_b64 v[88:89], 12, v[88:89]
	v_ashrrev_i32_e32 v73, 31, v72
	v_addc_co_u32_e32 v31, vcc, 0, v159, vcc
	v_cvt_pk_bf16_f32 v12, v12, v13
	v_cvt_pk_bf16_f32 v13, v14, v15
	v_cvt_pk_bf16_f32 v14, v8, v9
	v_cvt_pk_bf16_f32 v15, v10, v11
	global_store_dwordx4 v[158:159], v[108:111], off offset:256 sc1
	v_cvt_pk_bf16_f32 v95, v90, v91
	v_lshl_add_u64 v[88:89], s[36:37], 0, v[88:89]
	v_lshl_add_u64 v[108:109], v[104:105], 0, v[156:157]
	v_lshlrev_b64 v[72:73], 12, v[72:73]
	global_store_dwordx4 v[28:29], v[12:15], off offset:256 sc1
	global_store_dwordx4 v[108:109], v[92:95], off offset:256 sc1
	v_cvt_pk_bf16_f32 v79, v74, v75
	v_add_co_u32_e32 v14, vcc, 0xb0000, v158
	v_lshl_add_u64 v[92:93], v[88:89], 0, v[156:157]
	v_lshl_add_u64 v[72:73], s[36:37], 0, v[72:73]
	s_mov_b64 s[4:5], 0xb0000
	v_addc_co_u32_e32 v15, vcc, 0, v159, vcc
	v_cvt_pk_bf16_f32 v124, v124, v125
	v_cvt_pk_bf16_f32 v125, v126, v127
	v_cvt_pk_bf16_f32 v126, v120, v121
	v_cvt_pk_bf16_f32 v127, v122, v123
	v_cvt_pk_bf16_f32 v104, v116, v117
	v_cvt_pk_bf16_f32 v105, v118, v119
	v_cvt_pk_bf16_f32 v106, v112, v113
	v_cvt_pk_bf16_f32 v107, v114, v115
	v_cvt_pk_bf16_f32 v88, v100, v101
	v_cvt_pk_bf16_f32 v89, v102, v103
	v_cvt_pk_bf16_f32 v90, v96, v97
	v_cvt_pk_bf16_f32 v91, v98, v99
	global_store_dwordx4 v[92:93], v[76:79], off offset:256 sc1
	v_cvt_pk_bf16_f32 v74, v80, v81
	v_cvt_pk_bf16_f32 v75, v82, v83
	v_lshl_add_u64 v[76:77], v[72:73], 0, v[156:157]
	v_cvt_pk_bf16_f32 v72, v84, v85
	v_cvt_pk_bf16_f32 v73, v86, v87
	v_cvt_pk_bf16_f32 v71, v66, v67
	v_cvt_pk_bf16_f32 v63, v58, v59
	v_cvt_pk_bf16_f32 v40, v52, v53
	v_cvt_pk_bf16_f32 v41, v54, v55
	v_cvt_pk_bf16_f32 v42, v48, v49
	v_cvt_pk_bf16_f32 v43, v50, v51
	v_cvt_pk_bf16_f32 v24, v36, v37
	v_cvt_pk_bf16_f32 v25, v38, v39
	v_cvt_pk_bf16_f32 v26, v32, v33
	v_cvt_pk_bf16_f32 v27, v34, v35
	v_lshl_add_u64 v[12:13], v[158:159], 0, s[4:5]
	v_cvt_pk_bf16_f32 v8, v20, v21
	v_cvt_pk_bf16_f32 v9, v22, v23
	v_cvt_pk_bf16_f32 v10, v16, v17
	v_cvt_pk_bf16_f32 v11, v18, v19
	v_cvt_pk_bf16_f32 v4, v4, v5
	v_cvt_pk_bf16_f32 v5, v6, v7
	v_cvt_pk_bf16_f32 v6, v0, v1
	v_cvt_pk_bf16_f32 v7, v2, v3
	s_and_b64 vcc, exec, s[0:1]
	s_mov_b32 s69, s40
	s_mov_b32 s38, s42
	s_mov_b64 s[50:51], s[46:47]
	s_mov_b64 s[48:49], s[44:45]
	global_store_dwordx4 v[158:159], v[124:127], off sc1
	global_store_dwordx4 v[108:109], v[104:107], off sc1
	global_store_dwordx4 v[92:93], v[88:91], off sc1
	global_store_dwordx4 v[76:77], v[72:75], off sc1
	global_store_dwordx4 v[76:77], v[68:71], off offset:256 sc1
	global_store_dwordx4 v[56:57], v[60:63], off sc1
	global_store_dwordx4 v[46:47], v[40:43], off sc1
	global_store_dwordx4 v[30:31], v[24:27], off sc1
	global_store_dwordx4 v[14:15], v[8:11], off sc1
	global_store_dwordx4 v[12:13], v[4:7], off offset:256 sc1
	s_cbranch_vccz .LBB0_738
	s_waitcnt vmcnt(0)
	s_cmpk_gt_u32 s3, 0xff
	s_cbranch_scc1 .LBB0_749
	s_barrier

; DI void gemm_phase(LAS unsigned char* lds, const Gemm g, const StaticOrder& S, const EpiBf16& E) {
;     ...
;         const bool has_next = S.next(ui + 1, nxt);
;         const char* nA = has_next ? (const char*)g.A + (size_t)nxt.pm * tstep : cA; const char* nB = has_next ? (const char*)g.Bt + (size_t)nxt.pn * tstep : cB;
;         for (int t = 0; t < nt; t += 2) {
;             const bool last = (t == nt - 2);
;             const char* a1 = cA + (size_t)(t + 1) * kstep;
;             const char* a2 = last ? nA : cA + (size_t)(t + 2) * kstep; const char* b2 = last ? nB : cB + (size_t)(t + 2) * kstep;
;             const char* a3 = a2 + kstep; const char* b3 = b2 + kstep;
;     ...
; #pragma unroll
;         for (int a = 0; a < 2; ++a)
; #pragma unroll
;             for (int b = 0; b < 2; ++b)
; #pragma unroll
;                 for (int m = 0; m < 4; ++m)
; #pragma unroll
;                     for (int n = 0; n < 2; ++n) acc[a][b][m][n] = (f32x4){0.f, 0.f, 0.f, 0.f};
;         cur = nxt; cA = nA; cB = nB; ++ui;
.LBB0_836:
	s_ashr_i32 s41, s40, 31
	s_lshl_b64 s[4:5], s[40:41], 20
	v_cmp_lt_i64_e64 s[52:53], s[44:45], 32
	s_add_u32 s44, s24, s4
	s_addc_u32 s45, s26, s5
	s_and_b64 s[4:5], s[52:53], exec
	s_cselect_b32 s22, s45, s49
	s_cselect_b32 s41, s44, s48
	s_ashr_i32 s43, s42, 31
	s_lshl_b64 s[4:5], s[42:43], 20
	s_add_u32 s46, s27, s4
	s_addc_u32 s47, s30, s5
	s_and_b64 s[4:5], s[52:53], exec
	s_cselect_b32 s43, s47, s51
	s_cselect_b32 s71, s46, s50
	s_add_u32 s48, s48, 0x80080
	s_addc_u32 s49, s49, 0
	s_add_u32 s72, s50, 0x100
	v_mov_b32_e32 v0, 0
	s_addc_u32 s73, s51, 0
	s_mov_b32 s74, -2
	v_mov_b32_e32 v1, v0
	v_mov_b32_e32 v2, v0
	v_mov_b32_e32 v3, v0
	v_mov_b32_e32 v4, v0
	v_mov_b32_e32 v5, v0
	v_mov_b32_e32 v6, v0
	v_mov_b32_e32 v7, v0
	v_mov_b32_e32 v8, v0
	v_mov_b32_e32 v9, v0
	v_mov_b32_e32 v10, v0
	v_mov_b32_e32 v11, v0
	v_mov_b32_e32 v12, v0
	v_mov_b32_e32 v13, v0
	v_mov_b32_e32 v14, v0
	v_mov_b32_e32 v15, v0
	v_mov_b32_e32 v24, v0
	v_mov_b32_e32 v25, v0
	v_mov_b32_e32 v26, v0
	v_mov_b32_e32 v27, v0
	v_mov_b32_e32 v28, v0
	v_mov_b32_e32 v29, v0
	v_mov_b32_e32 v30, v0
	v_mov_b32_e32 v31, v0
	v_mov_b32_e32 v40, v0
	v_mov_b32_e32 v41, v0
	v_mov_b32_e32 v42, v0
	v_mov_b32_e32 v43, v0
	v_mov_b32_e32 v44, v0
	v_mov_b32_e32 v45, v0
	v_mov_b32_e32 v46, v0
	v_mov_b32_e32 v47, v0
	v_mov_b32_e32 v16, v0
	v_mov_b32_e32 v17, v0
	v_mov_b32_e32 v18, v0
	v_mov_b32_e32 v19, v0
	v_mov_b32_e32 v20, v0
	v_mov_b32_e32 v21, v0
	v_mov_b32_e32 v22, v0
	v_mov_b32_e32 v23, v0
	v_mov_b32_e32 v32, v0
	v_mov_b32_e32 v33, v0
	v_mov_b32_e32 v34, v0
	v_mov_b32_e32 v35, v0
	v_mov_b32_e32 v36, v0
	v_mov_b32_e32 v37, v0
	v_mov_b32_e32 v38, v0
	v_mov_b32_e32 v39, v0
	v_mov_b32_e32 v48, v0
	v_mov_b32_e32 v49, v0
	v_mov_b32_e32 v50, v0
	v_mov_b32_e32 v51, v0
	v_mov_b32_e32 v52, v0
	v_mov_b32_e32 v53, v0
	v_mov_b32_e32 v54, v0
	v_mov_b32_e32 v55, v0
	v_mov_b32_e32 v56, v0
	v_mov_b32_e32 v57, v0
	v_mov_b32_e32 v58, v0
	v_mov_b32_e32 v59, v0
	v_mov_b32_e32 v60, v0
	v_mov_b32_e32 v61, v0
	v_mov_b32_e32 v62, v0
	v_mov_b32_e32 v63, v0
	v_mov_b32_e32 v64, v0
	v_mov_b32_e32 v65, v0
	v_mov_b32_e32 v66, v0
	v_mov_b32_e32 v67, v0
	v_mov_b32_e32 v68, v0
	v_mov_b32_e32 v69, v0
	v_mov_b32_e32 v70, v0
	v_mov_b32_e32 v71, v0
	v_mov_b32_e32 v72, v0
	v_mov_b32_e32 v73, v0
	v_mov_b32_e32 v74, v0
	v_mov_b32_e32 v75, v0
	v_mov_b32_e32 v76, v0
	v_mov_b32_e32 v77, v0
	v_mov_b32_e32 v78, v0
	v_mov_b32_e32 v79, v0
	v_mov_b32_e32 v88, v0
	v_mov_b32_e32 v89, v0
	v_mov_b32_e32 v90, v0
	v_mov_b32_e32 v91, v0
	v_mov_b32_e32 v92, v0
	v_mov_b32_e32 v93, v0
	v_mov_b32_e32 v94, v0
	v_mov_b32_e32 v95, v0
	v_mov_b32_e32 v104, v0
	v_mov_b32_e32 v105, v0
	v_mov_b32_e32 v106, v0
	v_mov_b32_e32 v107, v0
	v_mov_b32_e32 v108, v0
	v_mov_b32_e32 v109, v0
	v_mov_b32_e32 v110, v0
	v_mov_b32_e32 v111, v0
	v_mov_b32_e32 v80, v0
	v_mov_b32_e32 v81, v0
	v_mov_b32_e32 v82, v0
	v_mov_b32_e32 v83, v0
	v_mov_b32_e32 v84, v0
	v_mov_b32_e32 v85, v0
	v_mov_b32_e32 v86, v0
	v_mov_b32_e32 v87, v0
	v_mov_b32_e32 v96, v0
	v_mov_b32_e32 v97, v0
	v_mov_b32_e32 v98, v0
	v_mov_b32_e32 v99, v0
	v_mov_b32_e32 v100, v0
	v_mov_b32_e32 v101, v0
	v_mov_b32_e32 v102, v0
	v_mov_b32_e32 v103, v0
	v_mov_b32_e32 v112, v0
	v_mov_b32_e32 v113, v0
	v_mov_b32_e32 v114, v0
	v_mov_b32_e32 v115, v0
	v_mov_b32_e32 v116, v0
	v_mov_b32_e32 v117, v0
	v_mov_b32_e32 v118, v0
	v_mov_b32_e32 v119, v0
	v_mov_b32_e32 v120, v0
	v_mov_b32_e32 v121, v0
	v_mov_b32_e32 v122, v0
	v_mov_b32_e32 v123, v0
	v_mov_b32_e32 v124, v0
	v_mov_b32_e32 v125, v0
	v_mov_b32_e32 v126, v0
	v_mov_b32_e32 v127, v0
	s_branch .Lk837_first

; #define PG8_STAGE(bufoff, gbase, voff) do { _Pragma("unroll") for (int _i = 0; _i < 2; ++_i) \
;         __builtin_amdgcn_global_load_lds((const unsigned*)((const char*)(gbase) + (voff)[_i]), (LAS unsigned*)(lds + (bufoff) + ldsw + _i * 8192), 16, 0, 0); } while (0)
; #define PG8_LDA(dst, b, h) do { _Pragma("unroll") for (int m = 0; m < 4; ++m) _Pragma("unroll") for (int k = 0; k < 2; ++k) dst[m][k] = *(const LAS bf16x8*)(lds + PG8_SA(b, h) + aoff + m * 2048 + k * 1024); } while (0)
; #define PG8_LDB(dst, b, h) do { _Pragma("unroll") for (int n = 0; n < 2; ++n) _Pragma("unroll") for (int k = 0; k < 2; ++k) dst[n][k] = *(const LAS bf16x8*)(lds + PG8_SB(b, h) + boff + n * 2048 + k * 1024); } while (0)
; #define PG8_MMA(ai, bj, At, Bt) do { __builtin_amdgcn_s_setprio(1); _Pragma("unroll") for (int m = 0; m < 4; ++m) _Pragma("unroll") for (int n = 0; n < 2; ++n) _Pragma("unroll") for (int k = 0; k < 2; ++k) \
;         acc[ai][bj][m][n] = __builtin_amdgcn_mfma_f32_16x16x32_bf16(Bt[n][k], At[m][k], acc[ai][bj][m][n], 0, 0, 0); __builtin_amdgcn_s_setprio(0); } while (0)
; #define PG8_WAIT_L(n) asm volatile("s_waitcnt lgkmcnt(" #n ")" ::: "memory")
; #define PG8_BAR __builtin_amdgcn_s_barrier()
; #define PG8_SCHED __builtin_amdgcn_sched_barrier(0)
; DI void gemm_phase(LAS unsigned char* lds, const Gemm g, const StaticOrder& S, const EpiBf16& E) {
;     ...
;         for (int t = 0; t < nt; t += 2) {
;             const bool last = (t == nt - 2);
;             const char* a1 = cA + (size_t)(t + 1) * kstep;
;             const char* a2 = last ? nA : cA + (size_t)(t + 2) * kstep; const char* b2 = last ? nB : cB + (size_t)(t + 2) * kstep;
;             const char* a3 = a2 + kstep; const char* b3 = b2 + kstep;
;             PG8_LDB(B0, 0, 0); PG8_SCHED; PG8_LDA(At, 0, 0); PG8_STAGE(PG8_SA(1, 1), a1 + hstep, voffA);
;             PG8_WAIT_L(8); PG8_BAR; PG8_WAIT_L(0); PG8_MMA(0, 0, At, B0); PG8_BAR; PG8_SCHED;
;             PG8_LDB(B1, 0, 1); PG8_STAGE(PG8_SB(0, 0), b2, voffB);
;             PG8_BAR; PG8_WAIT_L(0); PG8_MMA(0, 1, At, B1); PG8_BAR;
;             PG8_LDA(At, 0, 1); PG8_STAGE(PG8_SA(0, 0), a2, voffA);
;             PG8_BAR; PG8_WAIT_L(0); PG8_MMA(1, 0, At, B0); PG8_BAR; PG8_SCHED;
.Lk837_first:
	v_add_u32_e32 v134, s31, v153
	ds_read_b128 v[156:159], v134
	ds_read_b128 v[160:163], v134 offset:1024
	ds_read_b128 v[184:187], v134 offset:2048
	ds_read_b128 v[188:191], v134 offset:3072
	s_add_u32 s4, s48, 0xfff80080
	s_addc_u32 s5, s49, -1
	s_cmp_eq_u32 s74, 28
	s_cselect_b32 s53, s22, s5
	s_cselect_b32 s52, s41, s4
	s_cselect_b32 s51, s43, s73
	s_cselect_b32 s50, s71, s72
	v_lshl_add_u64 v[134:135], s[48:49], 0, v[148:149]
	s_add_i32 m0, s55, 0xc000
	ds_read_b128 v[192:195], v155
	ds_read_b128 v[196:199], v155 offset:1024
	ds_read_b128 v[200:203], v155 offset:2048
	ds_read_b128 v[204:207], v155 offset:3072
	ds_read_b128 v[208:211], v155 offset:4096
	ds_read_b128 v[212:215], v155 offset:5120
	ds_read_b128 v[216:219], v155 offset:6144
	ds_read_b128 v[224:227], v155 offset:7168
	global_load_lds_dwordx4 v[134:135], off
	v_lshl_add_u64 v[134:135], s[48:49], 0, v[150:151]
	s_add_i32 m0, s55, 0xe000
	s_nop 0
	global_load_lds_dwordx4 v[134:135], off
	s_waitcnt lgkmcnt(8)
	s_barrier
	s_waitcnt lgkmcnt(0)
	s_setprio 1
	s_waitcnt lgkmcnt(0)
	v_mfma_f32_16x16x32_bf16 v[124:127], v[156:159], v[192:195], v[124:127]
	v_mfma_f32_16x16x32_bf16 v[120:123], v[184:187], v[192:195], v[120:123]
	v_mfma_f32_16x16x32_bf16 v[116:119], v[156:159], v[200:203], v[116:119]
	v_mfma_f32_16x16x32_bf16 v[112:115], v[184:187], v[200:203], v[112:115]
	v_mfma_f32_16x16x32_bf16 v[100:103], v[156:159], v[208:211], v[100:103]
	v_mfma_f32_16x16x32_bf16 v[96:99], v[184:187], v[208:211], v[96:99]
	v_mfma_f32_16x16x32_bf16 v[84:87], v[156:159], v[216:219], v[84:87]
	v_mfma_f32_16x16x32_bf16 v[80:83], v[184:187], v[216:219], v[80:83]
	v_mfma_f32_16x16x32_bf16 v[124:127], v[160:163], v[196:199], v[124:127]
	v_mfma_f32_16x16x32_bf16 v[120:123], v[188:191], v[196:199], v[120:123]
	v_mfma_f32_16x16x32_bf16 v[116:119], v[160:163], v[204:207], v[116:119]
	v_mfma_f32_16x16x32_bf16 v[112:115], v[188:191], v[204:207], v[112:115]
	v_mfma_f32_16x16x32_bf16 v[100:103], v[160:163], v[212:215], v[100:103]
	v_mfma_f32_16x16x32_bf16 v[96:99], v[188:191], v[212:215], v[96:99]
	v_mfma_f32_16x16x32_bf16 v[84:87], v[160:163], v[224:227], v[84:87]
	v_mfma_f32_16x16x32_bf16 v[80:83], v[188:191], v[224:227], v[80:83]
	s_setprio 0
	s_barrier
	v_add_u32_e32 v134, s57, v153
	s_mov_b32 m0, s37
	ds_read_b128 v[228:231], v134
	ds_read_b128 v[232:235], v134 offset:1024
	ds_read_b128 v[236:239], v134 offset:2048
	ds_read_b128 v[240:243], v134 offset:3072
	v_lshl_add_u64 v[134:135], s[50:51], 0, v[132:133]
	global_load_lds_dwordx4 v[134:135], off
	v_lshl_add_u64 v[164:165], s[50:51], 0, v[146:147]
	s_mov_b32 m0, s54
	s_nop 0
	global_load_lds_dwordx4 v[164:165], off
	s_barrier
	s_waitcnt lgkmcnt(0)
	s_setprio 1
	s_waitcnt lgkmcnt(0)
	v_mfma_f32_16x16x32_bf16 v[108:111], v[228:231], v[192:195], v[108:111]
	v_mfma_f32_16x16x32_bf16 v[104:107], v[236:239], v[192:195], v[104:107]
	v_mfma_f32_16x16x32_bf16 v[92:95], v[228:231], v[200:203], v[92:95]
	v_mfma_f32_16x16x32_bf16 v[88:91], v[236:239], v[200:203], v[88:91]
	v_mfma_f32_16x16x32_bf16 v[76:79], v[228:231], v[208:211], v[76:79]
	v_mfma_f32_16x16x32_bf16 v[72:75], v[236:239], v[208:211], v[72:75]
	v_mfma_f32_16x16x32_bf16 v[68:71], v[228:231], v[216:219], v[68:71]
	v_mfma_f32_16x16x32_bf16 v[64:67], v[236:239], v[216:219], v[64:67]
	v_mfma_f32_16x16x32_bf16 v[108:111], v[232:235], v[196:199], v[108:111]
	v_mfma_f32_16x16x32_bf16 v[104:107], v[240:243], v[196:199], v[104:107]
	v_mfma_f32_16x16x32_bf16 v[92:95], v[232:235], v[204:207], v[92:95]
	v_mfma_f32_16x16x32_bf16 v[88:91], v[240:243], v[204:207], v[88:91]
	v_mfma_f32_16x16x32_bf16 v[76:79], v[232:235], v[212:215], v[76:79]
	v_mfma_f32_16x16x32_bf16 v[72:75], v[240:243], v[212:215], v[72:75]
	v_mfma_f32_16x16x32_bf16 v[68:71], v[232:235], v[224:227], v[68:71]
	v_mfma_f32_16x16x32_bf16 v[64:67], v[240:243], v[224:227], v[64:67]
	s_setprio 0
	s_mov_b32 m0, s55
	v_lshl_add_u64 v[244:245], s[52:53], 0, v[142:143]
	s_barrier
	ds_read_b128 v[192:195], v155 offset:16384
	ds_read_b128 v[196:199], v155 offset:17408
	ds_read_b128 v[200:203], v155 offset:18432
	ds_read_b128 v[204:207], v155 offset:19456
	ds_read_b128 v[208:211], v155 offset:20480
	ds_read_b128 v[212:215], v155 offset:21504
	ds_read_b128 v[216:219], v155 offset:22528
	ds_read_b128 v[224:227], v155 offset:23552
	global_load_lds_dwordx4 v[244:245], off
	v_lshl_add_u64 v[246:247], s[52:53], 0, v[144:145]
	s_mov_b32 m0, s56
	s_nop 0
	global_load_lds_dwordx4 v[246:247], off
	s_barrier
	s_waitcnt lgkmcnt(0)
	s_setprio 1
	s_waitcnt lgkmcnt(0)
	v_mfma_f32_16x16x32_bf16 v[60:63], v[156:159], v[192:195], v[60:63]
	v_mfma_f32_16x16x32_bf16 v[56:59], v[184:187], v[192:195], v[56:59]
	v_mfma_f32_16x16x32_bf16 v[52:55], v[156:159], v[200:203], v[52:55]
	v_mfma_f32_16x16x32_bf16 v[48:51], v[184:187], v[200:203], v[48:51]
	v_mfma_f32_16x16x32_bf16 v[36:39], v[156:159], v[208:211], v[36:39]
	v_mfma_f32_16x16x32_bf16 v[32:35], v[184:187], v[208:211], v[32:35]
	v_mfma_f32_16x16x32_bf16 v[20:23], v[156:159], v[216:219], v[20:23]
	v_mfma_f32_16x16x32_bf16 v[16:19], v[184:187], v[216:219], v[16:19]
	v_mfma_f32_16x16x32_bf16 v[60:63], v[160:163], v[196:199], v[60:63]
	v_mfma_f32_16x16x32_bf16 v[56:59], v[188:191], v[196:199], v[56:59]
	v_mfma_f32_16x16x32_bf16 v[52:55], v[160:163], v[204:207], v[52:55]
	v_mfma_f32_16x16x32_bf16 v[48:51], v[188:191], v[204:207], v[48:51]
	v_mfma_f32_16x16x32_bf16 v[36:39], v[160:163], v[212:215], v[36:39]
	v_mfma_f32_16x16x32_bf16 v[32:35], v[188:191], v[212:215], v[32:35]
	v_mfma_f32_16x16x32_bf16 v[20:23], v[160:163], v[224:227], v[20:23]
	v_mfma_f32_16x16x32_bf16 v[16:19], v[188:191], v[224:227], v[16:19]
	s_setprio 0
	s_barrier
; #define PG8_STAGE(bufoff, gbase, voff) do { _Pragma("unroll") for (int _i = 0; _i < 2; ++_i) \
;         __builtin_amdgcn_global_load_lds((const unsigned*)((const char*)(gbase) + (voff)[_i]), (LAS unsigned*)(lds + (bufoff) + ldsw + _i * 8192), 16, 0, 0); } while (0)
; #define PG8_LDA(dst, b, h) do { _Pragma("unroll") for (int m = 0; m < 4; ++m) _Pragma("unroll") for (int k = 0; k < 2; ++k) dst[m][k] = *(const LAS bf16x8*)(lds + PG8_SA(b, h) + aoff + m * 2048 + k * 1024); } while (0)
; #define PG8_LDB(dst, b, h) do { _Pragma("unroll") for (int n = 0; n < 2; ++n) _Pragma("unroll") for (int k = 0; k < 2; ++k) dst[n][k] = *(const LAS bf16x8*)(lds + PG8_SB(b, h) + boff + n * 2048 + k * 1024); } while (0)
; #define PG8_MMA(ai, bj, At, Bt) do { __builtin_amdgcn_s_setprio(1); _Pragma("unroll") for (int m = 0; m < 4; ++m) _Pragma("unroll") for (int n = 0; n < 2; ++n) _Pragma("unroll") for (int k = 0; k < 2; ++k) \
;         acc[ai][bj][m][n] = __builtin_amdgcn_mfma_f32_16x16x32_bf16(Bt[n][k], At[m][k], acc[ai][bj][m][n], 0, 0, 0); __builtin_amdgcn_s_setprio(0); } while (0)
; #define PG8_WAIT_V(n) asm volatile("s_waitcnt vmcnt(" #n ")" ::: "memory")
; #define PG8_WAIT_L(n) asm volatile("s_waitcnt lgkmcnt(" #n ")" ::: "memory")
; #define PG8_BAR __builtin_amdgcn_s_barrier()
; #define PG8_SCHED __builtin_amdgcn_sched_barrier(0)
; DI void gemm_phase(LAS unsigned char* lds, const Gemm g, const StaticOrder& S, const EpiBf16& E) {
;     ...
;             PG8_STAGE(PG8_SB(0, 1), b2 + hstep, voffB);
;             PG8_WAIT_V(6); PG8_BAR; PG8_MMA(1, 1, At, B1); PG8_BAR;
;             PG8_LDB(B0, 1, 0); PG8_SCHED; PG8_LDA(At, 1, 0); PG8_STAGE(PG8_SA(0, 1), a2 + hstep, voffA);
;             PG8_WAIT_L(8); PG8_BAR; PG8_WAIT_L(0); PG8_MMA(0, 0, At, B0); PG8_BAR; PG8_SCHED;
;             PG8_LDB(B1, 1, 1); PG8_STAGE(PG8_SB(1, 0), b3, voffB);
;             PG8_BAR; PG8_WAIT_L(0); PG8_MMA(0, 1, At, B1); PG8_BAR;
;             PG8_LDA(At, 1, 1); PG8_STAGE(PG8_SA(1, 0), a3, voffA);
;             PG8_BAR; PG8_WAIT_L(0); PG8_MMA(1, 0, At, B0); PG8_BAR; PG8_SCHED;
;             PG8_STAGE(PG8_SB(1, 1), b3 + hstep, voffB);
	s_add_u32 s4, s50, 0x80000
	s_addc_u32 s5, s51, 0
	s_mov_b32 m0, s58
	v_lshl_add_u64 v[156:157], s[4:5], 0, v[132:133]
	global_load_lds_dwordx4 v[156:157], off
	v_lshl_add_u64 v[156:157], s[4:5], 0, v[146:147]
	s_mov_b32 m0, s59
	s_nop 0
	global_load_lds_dwordx4 v[156:157], off
	s_waitcnt vmcnt(6)
	s_barrier
	s_setprio 1
	v_mfma_f32_16x16x32_bf16 v[44:47], v[228:231], v[192:195], v[44:47]
	v_mfma_f32_16x16x32_bf16 v[40:43], v[236:239], v[192:195], v[40:43]
	v_mfma_f32_16x16x32_bf16 v[28:31], v[228:231], v[200:203], v[28:31]
	v_mfma_f32_16x16x32_bf16 v[24:27], v[236:239], v[200:203], v[24:27]
	v_mfma_f32_16x16x32_bf16 v[12:15], v[228:231], v[208:211], v[12:15]
	v_mfma_f32_16x16x32_bf16 v[8:11], v[236:239], v[208:211], v[8:11]
	v_mfma_f32_16x16x32_bf16 v[4:7], v[228:231], v[216:219], v[4:7]
	v_mfma_f32_16x16x32_bf16 v[0:3], v[236:239], v[216:219], v[0:3]
	v_mfma_f32_16x16x32_bf16 v[44:47], v[232:235], v[196:199], v[44:47]
	v_mfma_f32_16x16x32_bf16 v[40:43], v[240:243], v[196:199], v[40:43]
	v_mfma_f32_16x16x32_bf16 v[28:31], v[232:235], v[204:207], v[28:31]
	v_mfma_f32_16x16x32_bf16 v[24:27], v[240:243], v[204:207], v[24:27]
	v_mfma_f32_16x16x32_bf16 v[12:15], v[232:235], v[212:215], v[12:15]
	v_mfma_f32_16x16x32_bf16 v[8:11], v[240:243], v[212:215], v[8:11]
	v_mfma_f32_16x16x32_bf16 v[4:7], v[232:235], v[224:227], v[4:7]
	v_mfma_f32_16x16x32_bf16 v[0:3], v[240:243], v[224:227], v[0:3]
	s_setprio 0
	v_add_u32_e32 v183, s62, v153
	s_barrier
	ds_read_b128 v[156:159], v183
	ds_read_b128 v[160:163], v183 offset:1024
	ds_read_b128 v[184:187], v183 offset:2048
	ds_read_b128 v[188:191], v183 offset:3072
	s_add_u32 s4, s52, 0x80000
	s_addc_u32 s5, s53, 0
	s_mov_b32 m0, s60
	v_lshl_add_u64 v[228:229], s[4:5], 0, v[142:143]
	ds_read_b128 v[192:195], v155 offset:32768
	ds_read_b128 v[196:199], v155 offset:33792
	ds_read_b128 v[200:203], v155 offset:34816
	ds_read_b128 v[204:207], v155 offset:35840
	ds_read_b128 v[208:211], v155 offset:36864
	ds_read_b128 v[212:215], v155 offset:37888
	ds_read_b128 v[216:219], v155 offset:38912
	ds_read_b128 v[224:227], v155 offset:39936
	global_load_lds_dwordx4 v[228:229], off
	v_lshl_add_u64 v[228:229], s[4:5], 0, v[144:145]
	s_mov_b32 m0, s61
	s_nop 0
	global_load_lds_dwordx4 v[228:229], off
	s_waitcnt lgkmcnt(8)
	s_barrier
	s_waitcnt lgkmcnt(0)
	s_setprio 1
	s_waitcnt lgkmcnt(0)
	v_mfma_f32_16x16x32_bf16 v[124:127], v[156:159], v[192:195], v[124:127]
	v_mfma_f32_16x16x32_bf16 v[120:123], v[184:187], v[192:195], v[120:123]
	v_mfma_f32_16x16x32_bf16 v[116:119], v[156:159], v[200:203], v[116:119]
	v_mfma_f32_16x16x32_bf16 v[112:115], v[184:187], v[200:203], v[112:115]
	v_mfma_f32_16x16x32_bf16 v[100:103], v[156:159], v[208:211], v[100:103]
	v_mfma_f32_16x16x32_bf16 v[96:99], v[184:187], v[208:211], v[96:99]
	v_mfma_f32_16x16x32_bf16 v[84:87], v[156:159], v[216:219], v[84:87]
	v_mfma_f32_16x16x32_bf16 v[80:83], v[184:187], v[216:219], v[80:83]
	v_mfma_f32_16x16x32_bf16 v[124:127], v[160:163], v[196:199], v[124:127]
	v_mfma_f32_16x16x32_bf16 v[120:123], v[188:191], v[196:199], v[120:123]
	v_mfma_f32_16x16x32_bf16 v[116:119], v[160:163], v[204:207], v[116:119]
	v_mfma_f32_16x16x32_bf16 v[112:115], v[188:191], v[204:207], v[112:115]
	v_mfma_f32_16x16x32_bf16 v[100:103], v[160:163], v[212:215], v[100:103]
	v_mfma_f32_16x16x32_bf16 v[96:99], v[188:191], v[212:215], v[96:99]
	v_mfma_f32_16x16x32_bf16 v[84:87], v[160:163], v[224:227], v[84:87]
	v_mfma_f32_16x16x32_bf16 v[80:83], v[188:191], v[224:227], v[80:83]
	s_setprio 0
	s_barrier
	s_mov_b32 m0, s63
	v_add_u32_e32 v183, s67, v153
	v_lshl_add_u64 v[134:135], v[134:135], 0, s[34:35]
	ds_read_b128 v[228:231], v183
	ds_read_b128 v[232:235], v183 offset:1024
	ds_read_b128 v[236:239], v183 offset:2048
	ds_read_b128 v[240:243], v183 offset:3072
	global_load_lds_dwordx4 v[134:135], off
	v_lshl_add_u64 v[134:135], v[164:165], 0, s[34:35]
	s_mov_b32 m0, s64
	s_nop 0
	global_load_lds_dwordx4 v[134:135], off
	s_barrier
	s_waitcnt lgkmcnt(0)
	s_setprio 1
	s_waitcnt lgkmcnt(0)
	v_mfma_f32_16x16x32_bf16 v[108:111], v[228:231], v[192:195], v[108:111]
	v_mfma_f32_16x16x32_bf16 v[104:107], v[236:239], v[192:195], v[104:107]
	v_mfma_f32_16x16x32_bf16 v[92:95], v[228:231], v[200:203], v[92:95]
	v_mfma_f32_16x16x32_bf16 v[88:91], v[236:239], v[200:203], v[88:91]
	v_mfma_f32_16x16x32_bf16 v[76:79], v[228:231], v[208:211], v[76:79]
	v_mfma_f32_16x16x32_bf16 v[72:75], v[236:239], v[208:211], v[72:75]
	v_mfma_f32_16x16x32_bf16 v[68:71], v[228:231], v[216:219], v[68:71]
	v_mfma_f32_16x16x32_bf16 v[64:67], v[236:239], v[216:219], v[64:67]
	v_mfma_f32_16x16x32_bf16 v[108:111], v[232:235], v[196:199], v[108:111]
	v_mfma_f32_16x16x32_bf16 v[104:107], v[240:243], v[196:199], v[104:107]
	v_mfma_f32_16x16x32_bf16 v[92:95], v[232:235], v[204:207], v[92:95]
	v_mfma_f32_16x16x32_bf16 v[88:91], v[240:243], v[204:207], v[88:91]
	v_mfma_f32_16x16x32_bf16 v[76:79], v[232:235], v[212:215], v[76:79]
	v_mfma_f32_16x16x32_bf16 v[72:75], v[240:243], v[212:215], v[72:75]
	v_mfma_f32_16x16x32_bf16 v[68:71], v[232:235], v[224:227], v[68:71]
	v_mfma_f32_16x16x32_bf16 v[64:67], v[240:243], v[224:227], v[64:67]
	s_setprio 0
	s_mov_b32 m0, s65
	v_lshl_add_u64 v[134:135], v[244:245], 0, s[34:35]
	s_barrier
	ds_read_b128 v[192:195], v155 offset:49152
	ds_read_b128 v[196:199], v155 offset:50176
	ds_read_b128 v[200:203], v155 offset:51200
	ds_read_b128 v[204:207], v155 offset:52224
	ds_read_b128 v[208:211], v155 offset:53248
	ds_read_b128 v[212:215], v155 offset:54272
	ds_read_b128 v[216:219], v155 offset:55296
	ds_read_b128 v[224:227], v155 offset:56320
	global_load_lds_dwordx4 v[134:135], off
	v_lshl_add_u64 v[134:135], v[246:247], 0, s[34:35]
	s_mov_b32 m0, s66
	s_nop 0
	global_load_lds_dwordx4 v[134:135], off
	s_barrier
; #define PG8_STAGE(bufoff, gbase, voff) do { _Pragma("unroll") for (int _i = 0; _i < 2; ++_i) \
;         __builtin_amdgcn_global_load_lds((const unsigned*)((const char*)(gbase) + (voff)[_i]), (LAS unsigned*)(lds + (bufoff) + ldsw + _i * 8192), 16, 0, 0); } while (0)
; #define PG8_MMA(ai, bj, At, Bt) do { __builtin_amdgcn_s_setprio(1); _Pragma("unroll") for (int m = 0; m < 4; ++m) _Pragma("unroll") for (int n = 0; n < 2; ++n) _Pragma("unroll") for (int k = 0; k < 2; ++k) \
;         acc[ai][bj][m][n] = __builtin_amdgcn_mfma_f32_16x16x32_bf16(Bt[n][k], At[m][k], acc[ai][bj][m][n], 0, 0, 0); __builtin_amdgcn_s_setprio(0); } while (0)
; #define PG8_WAIT_V(n) asm volatile("s_waitcnt vmcnt(" #n ")" ::: "memory")
; #define PG8_WAIT_L(n) asm volatile("s_waitcnt lgkmcnt(" #n ")" ::: "memory")
; #define PG8_BAR __builtin_amdgcn_s_barrier()
; #define PG8_SCHED __builtin_amdgcn_sched_barrier(0)
; DI void gemm_phase(LAS unsigned char* lds, const Gemm g, const StaticOrder& S, const EpiBf16& E) {
;     ...
;         for (int t = 0; t < nt; t += 2) {
;     ...
;             PG8_BAR; PG8_WAIT_L(0); PG8_MMA(1, 0, At, B0); PG8_BAR; PG8_SCHED;
;             PG8_STAGE(PG8_SB(1, 1), b3 + hstep, voffB);
;             PG8_WAIT_V(6); PG8_BAR; PG8_MMA(1, 1, At, B1); PG8_BAR;
	s_waitcnt lgkmcnt(0)
	s_setprio 1
	s_waitcnt lgkmcnt(0)
	v_mfma_f32_16x16x32_bf16 v[60:63], v[156:159], v[192:195], v[60:63]
	v_mfma_f32_16x16x32_bf16 v[56:59], v[184:187], v[192:195], v[56:59]
	v_mfma_f32_16x16x32_bf16 v[52:55], v[156:159], v[200:203], v[52:55]
	v_mfma_f32_16x16x32_bf16 v[48:51], v[184:187], v[200:203], v[48:51]
	v_mfma_f32_16x16x32_bf16 v[36:39], v[156:159], v[208:211], v[36:39]
	v_mfma_f32_16x16x32_bf16 v[32:35], v[184:187], v[208:211], v[32:35]
	v_mfma_f32_16x16x32_bf16 v[20:23], v[156:159], v[216:219], v[20:23]
	v_mfma_f32_16x16x32_bf16 v[16:19], v[184:187], v[216:219], v[16:19]
	v_mfma_f32_16x16x32_bf16 v[60:63], v[160:163], v[196:199], v[60:63]
	v_mfma_f32_16x16x32_bf16 v[56:59], v[188:191], v[196:199], v[56:59]
	v_mfma_f32_16x16x32_bf16 v[52:55], v[160:163], v[204:207], v[52:55]
	v_mfma_f32_16x16x32_bf16 v[48:51], v[188:191], v[204:207], v[48:51]
	v_mfma_f32_16x16x32_bf16 v[36:39], v[160:163], v[212:215], v[36:39]
	v_mfma_f32_16x16x32_bf16 v[32:35], v[188:191], v[212:215], v[32:35]
	v_mfma_f32_16x16x32_bf16 v[20:23], v[160:163], v[224:227], v[20:23]
	v_mfma_f32_16x16x32_bf16 v[16:19], v[188:191], v[224:227], v[16:19]
	s_setprio 0
	s_barrier
	s_add_u32 s4, s50, 0x80080
	s_addc_u32 s5, s51, 0
	s_mov_b32 m0, s68
	v_lshl_add_u64 v[134:135], s[4:5], 0, v[132:133]
	global_load_lds_dwordx4 v[134:135], off
	v_lshl_add_u64 v[134:135], s[4:5], 0, v[146:147]
	s_mov_b32 m0, s69
	s_nop 0
	global_load_lds_dwordx4 v[134:135], off
	s_waitcnt vmcnt(6)
	s_barrier
	s_setprio 1
	v_mfma_f32_16x16x32_bf16 v[44:47], v[228:231], v[192:195], v[44:47]
	v_mfma_f32_16x16x32_bf16 v[40:43], v[236:239], v[192:195], v[40:43]
	v_mfma_f32_16x16x32_bf16 v[28:31], v[228:231], v[200:203], v[28:31]
	v_mfma_f32_16x16x32_bf16 v[24:27], v[236:239], v[200:203], v[24:27]
	v_mfma_f32_16x16x32_bf16 v[12:15], v[228:231], v[208:211], v[12:15]
	v_mfma_f32_16x16x32_bf16 v[8:11], v[236:239], v[208:211], v[8:11]
	v_mfma_f32_16x16x32_bf16 v[4:7], v[228:231], v[216:219], v[4:7]
	v_mfma_f32_16x16x32_bf16 v[0:3], v[236:239], v[216:219], v[0:3]
	v_mfma_f32_16x16x32_bf16 v[44:47], v[232:235], v[196:199], v[44:47]
	v_mfma_f32_16x16x32_bf16 v[40:43], v[240:243], v[196:199], v[40:43]
	v_mfma_f32_16x16x32_bf16 v[28:31], v[232:235], v[204:207], v[28:31]
	v_mfma_f32_16x16x32_bf16 v[24:27], v[240:243], v[204:207], v[24:27]
	v_mfma_f32_16x16x32_bf16 v[12:15], v[232:235], v[212:215], v[12:15]
	v_mfma_f32_16x16x32_bf16 v[8:11], v[240:243], v[212:215], v[8:11]
	v_mfma_f32_16x16x32_bf16 v[4:7], v[232:235], v[224:227], v[4:7]
	v_mfma_f32_16x16x32_bf16 v[0:3], v[240:243], v[224:227], v[0:3]
	s_setprio 0
	s_add_i32 s74, s74, 2
	s_add_u32 s48, s48, 0x100
	s_addc_u32 s49, s49, 0
	s_add_u32 s72, s72, 0x100
	s_addc_u32 s73, s73, 0
	s_cmp_gt_u32 s74, 29
	s_cbranch_scc0 .LBB0_837
	s_barrier
; #define PG8_WAIT_V(n) asm volatile("s_waitcnt vmcnt(" #n ")" ::: "memory")
; #define PG8_BAR __builtin_amdgcn_s_barrier()
;     DI void operator()(const f32x4 (&acc)[2][2][4][2], const Unit& u, int wr, int wc, int fr, int fq) const {
;         const int row0 = u.pm * BM + wr * 64 + fr; const int col0 = u.pn * BM + wc * 32 + 8 * fq;
; #pragma unroll
;         for (int ai = 0; ai < 2; ++ai)
; #pragma unroll
;             for (int m = 0; m < 4; ++m) { bf16_t* rowp = O + (size_t)(row0 + ai * HALF + m * 16) * ldc + col0;
; #pragma unroll
;                 for (int bj = 0; bj < 2; ++bj) { const f32x4 v0 = acc[ai][bj][m][0], v1 = acc[ai][bj][m][1];
;                     u32x4 w; w.x = pk2(v0[0], v0[1]); w.y = pk2(v0[2], v0[3]); w.z = pk2(v1[0], v1[1]); w.w = pk2(v1[2], v1[3]);
;                     *(u32x4*)(rowp + bj * HALF) = w; } }
;     }
; DI void gemm_phase(LAS unsigned char* lds, const Gemm g, const StaticOrder& S, const EpiBf16& E) {
;     ...
;         E(acc, cur, wr, wc, fr, fq);
;         if (!has_next) break;
; #pragma unroll
;         for (int a = 0; a < 2; ++a)
; #pragma unroll
;             for (int b = 0; b < 2; ++b)
; #pragma unroll
;                 for (int m = 0; m < 4; ++m)
; #pragma unroll
;                     for (int n = 0; n < 2; ++n) acc[a][b][m][n] = (f32x4){0.f, 0.f, 0.f, 0.f};
;         cur = nxt; cA = nA; cB = nB; ++ui;
;     }
;     PG8_WAIT_V(0);
;     if (wr == 0) PG8_BAR;
;     PG8_BAR;
	v_lshl_add_u32 v134, s36, 8, v152
	v_lshl_or_b32 v156, s70, 8, v154
	v_ashrrev_i32_e32 v135, 31, v134
	v_ashrrev_i32_e32 v157, 31, v156
	v_lshlrev_b64 v[158:159], 12, v[134:135]
	v_lshl_add_u64 v[158:159], s[0:1], 0, v[158:159]
	v_lshlrev_b64 v[156:157], 1, v[156:157]
	v_lshl_add_u64 v[158:159], v[158:159], 0, v[156:157]
	s_mov_b64 s[4:5], 0x80000
	v_cvt_pk_bf16_f32 v68, v68, v69
	v_cvt_pk_bf16_f32 v69, v70, v71
	v_cvt_pk_bf16_f32 v70, v64, v65
	v_lshl_add_u64 v[64:65], v[158:159], 0, s[4:5]
	s_mov_b32 s4, 0x80000
	v_cvt_pk_bf16_f32 v60, v60, v61
	v_cvt_pk_bf16_f32 v61, v62, v63
	v_cvt_pk_bf16_f32 v62, v56, v57
	v_add_co_u32_e32 v56, vcc, s4, v158
	v_cvt_pk_bf16_f32 v44, v44, v45
	v_cvt_pk_bf16_f32 v45, v46, v47
	v_cvt_pk_bf16_f32 v46, v40, v41
	v_cvt_pk_bf16_f32 v47, v42, v43
	s_mov_b64 s[4:5], 0x90000
	v_addc_co_u32_e32 v57, vcc, 0, v159, vcc
	global_store_dwordx4 v[64:65], v[44:47], off offset:256 sc1
	v_cvt_pk_bf16_f32 v108, v108, v109
	v_cvt_pk_bf16_f32 v109, v110, v111
	v_lshl_add_u64 v[44:45], v[158:159], 0, s[4:5]
	s_mov_b32 s4, 0x90000
	v_cvt_pk_bf16_f32 v110, v104, v105
	v_or_b32_e32 v104, 16, v134
	v_add_co_u32_e32 v46, vcc, s4, v158
	v_cvt_pk_bf16_f32 v28, v28, v29
	v_cvt_pk_bf16_f32 v29, v30, v31
	v_cvt_pk_bf16_f32 v30, v24, v25
	v_cvt_pk_bf16_f32 v31, v26, v27
	s_mov_b64 s[4:5], 0xa0000
	v_ashrrev_i32_e32 v105, 31, v104
	v_cvt_pk_bf16_f32 v92, v92, v93
	v_cvt_pk_bf16_f32 v93, v94, v95
	v_cvt_pk_bf16_f32 v94, v88, v89
	v_or_b32_e32 v88, 32, v134
	v_addc_co_u32_e32 v47, vcc, 0, v159, vcc
	global_store_dwordx4 v[44:45], v[28:31], off offset:256 sc1
	v_lshlrev_b64 v[104:105], 12, v[104:105]
	v_ashrrev_i32_e32 v89, 31, v88
	v_lshl_add_u64 v[28:29], v[158:159], 0, s[4:5]
	s_mov_b32 s4, 0xa0000
	v_cvt_pk_bf16_f32 v76, v76, v77
	v_cvt_pk_bf16_f32 v77, v78, v79
	v_cvt_pk_bf16_f32 v78, v72, v73
	v_or_b32_e32 v72, 48, v134
	v_add_co_u32_e32 v30, vcc, s4, v158
	v_cvt_pk_bf16_f32 v111, v106, v107
	v_lshl_add_u64 v[104:105], s[0:1], 0, v[104:105]
	v_lshlrev_b64 v[88:89], 12, v[88:89]
	v_ashrrev_i32_e32 v73, 31, v72
	v_addc_co_u32_e32 v31, vcc, 0, v159, vcc
	v_cvt_pk_bf16_f32 v12, v12, v13
	v_cvt_pk_bf16_f32 v13, v14, v15
	v_cvt_pk_bf16_f32 v14, v8, v9
	v_cvt_pk_bf16_f32 v15, v10, v11
	global_store_dwordx4 v[158:159], v[108:111], off offset:256 sc1
	v_cvt_pk_bf16_f32 v95, v90, v91
	v_lshl_add_u64 v[88:89], s[0:1], 0, v[88:89]
	v_lshl_add_u64 v[108:109], v[104:105], 0, v[156:157]
	v_lshlrev_b64 v[72:73], 12, v[72:73]
	global_store_dwordx4 v[28:29], v[12:15], off offset:256 sc1
	global_store_dwordx4 v[108:109], v[92:95], off offset:256 sc1
	v_cvt_pk_bf16_f32 v79, v74, v75
	v_add_co_u32_e32 v14, vcc, 0xb0000, v158
	v_lshl_add_u64 v[92:93], v[88:89], 0, v[156:157]
	v_lshl_add_u64 v[72:73], s[0:1], 0, v[72:73]
	s_mov_b64 s[4:5], 0xb0000
	v_addc_co_u32_e32 v15, vcc, 0, v159, vcc
	v_cvt_pk_bf16_f32 v124, v124, v125
	v_cvt_pk_bf16_f32 v125, v126, v127
	v_cvt_pk_bf16_f32 v126, v120, v121
	v_cvt_pk_bf16_f32 v127, v122, v123
	v_cvt_pk_bf16_f32 v104, v116, v117
	v_cvt_pk_bf16_f32 v105, v118, v119
	v_cvt_pk_bf16_f32 v106, v112, v113
	v_cvt_pk_bf16_f32 v107, v114, v115
	v_cvt_pk_bf16_f32 v88, v100, v101
	v_cvt_pk_bf16_f32 v89, v102, v103
	v_cvt_pk_bf16_f32 v90, v96, v97
	v_cvt_pk_bf16_f32 v91, v98, v99
	global_store_dwordx4 v[92:93], v[76:79], off offset:256 sc1
	v_cvt_pk_bf16_f32 v74, v80, v81
	v_cvt_pk_bf16_f32 v75, v82, v83
	v_lshl_add_u64 v[76:77], v[72:73], 0, v[156:157]
	v_cvt_pk_bf16_f32 v72, v84, v85
	v_cvt_pk_bf16_f32 v73, v86, v87
	v_cvt_pk_bf16_f32 v71, v66, v67
	v_cvt_pk_bf16_f32 v63, v58, v59
	v_cvt_pk_bf16_f32 v40, v52, v53
	v_cvt_pk_bf16_f32 v41, v54, v55
	v_cvt_pk_bf16_f32 v42, v48, v49
	v_cvt_pk_bf16_f32 v43, v50, v51
	v_cvt_pk_bf16_f32 v24, v36, v37
	v_cvt_pk_bf16_f32 v25, v38, v39
	v_cvt_pk_bf16_f32 v26, v32, v33
	v_cvt_pk_bf16_f32 v27, v34, v35
	v_lshl_add_u64 v[12:13], v[158:159], 0, s[4:5]
	v_cvt_pk_bf16_f32 v8, v20, v21
	v_cvt_pk_bf16_f32 v9, v22, v23
	v_cvt_pk_bf16_f32 v10, v16, v17
	v_cvt_pk_bf16_f32 v11, v18, v19
	v_cvt_pk_bf16_f32 v4, v4, v5
	v_cvt_pk_bf16_f32 v5, v6, v7
	v_cvt_pk_bf16_f32 v6, v0, v1
	v_cvt_pk_bf16_f32 v7, v2, v3
	s_and_b64 vcc, exec, s[38:39]
	s_mov_b32 s70, s42
	s_mov_b32 s36, s40
	s_mov_b64 s[50:51], s[46:47]
	s_mov_b64 s[48:49], s[44:45]
	global_store_dwordx4 v[158:159], v[124:127], off sc1
	global_store_dwordx4 v[108:109], v[104:107], off sc1
	global_store_dwordx4 v[92:93], v[88:91], off sc1
	global_store_dwordx4 v[76:77], v[72:75], off sc1
	global_store_dwordx4 v[76:77], v[68:71], off offset:256 sc1
	global_store_dwordx4 v[56:57], v[60:63], off sc1
	global_store_dwordx4 v[46:47], v[40:43], off sc1
	global_store_dwordx4 v[30:31], v[24:27], off sc1
	global_store_dwordx4 v[14:15], v[8:11], off sc1
	global_store_dwordx4 v[12:13], v[4:7], off offset:256 sc1
	s_cbranch_vccz .LBB0_830
	s_waitcnt vmcnt(0)
	s_cmpk_gt_u32 s2, 0xff
	s_cbranch_scc1 .LBB0_841
	s_barrier
